# P4 tile body rewritten by hand: continuous LDS-DMA schedule with counted vmcnt, conv weights hoisted out of the epilogue, next tile k-tile0 staged under the epilogue; P3/P5 residual epilogues pipeline
# speedup vs baseline: 1.0525x; 1.0525x over previous
.LBB0_1087:
	s_mul_hi_i32 s2, s49, 0x2e8ba2e9
	s_lshr_b32 s3, s2, 31
	s_ashr_i32 s2, s2, 6
	s_add_i32 s2, s2, s3
	s_lshl_b32 s3, s2, 4
	s_sub_i32 s4, s7, s3
	s_min_i32 s4, s4, 16
	s_abs_i32 s5, s4
	v_cvt_f32_u32_e32 v3, s5
	s_sub_i32 s20, 0, s5
	s_mulk_i32 s2, 0xfea0
	s_add_i32 s2, s2, s49
	v_rcp_iflag_f32_e32 v3, v3
	s_abs_i32 s19, s2
	s_xor_b32 s18, s2, s4
	s_ashr_i32 s18, s18, 31
	v_mul_f32_e32 v3, 0x4f7ffffe, v3
	v_cvt_u32_f32_e32 v3, v3
	v_mov_b32_e32 v1, v222
	v_mov_b32_e32 v9, v211
	v_readfirstlane_b32 s21, v3
	s_mul_i32 s20, s20, s21
	s_mul_hi_u32 s20, s21, s20
	s_add_i32 s21, s21, s20
	s_mul_hi_u32 s20, s19, s21
	s_mul_i32 s21, s20, s5
	s_sub_i32 s19, s19, s21
	s_add_i32 s21, s20, 1
	s_sub_i32 s22, s19, s5
	s_cmp_ge_u32 s19, s5
	s_cselect_b32 s20, s21, s20
	s_cselect_b32 s19, s22, s19
	s_add_i32 s21, s20, 1
	s_cmp_ge_u32 s19, s5
	s_cselect_b32 s5, s21, s20
	s_xor_b32 s5, s5, s18
	s_sub_i32 s18, s5, s18
	s_mul_i32 s4, s18, s4
	s_sub_i32 s2, s2, s4
	s_add_i32 s2, s2, s3
	s_mul_i32 s28, s2, 0xfe
	s_add_i32 s28, s28, -1
	v_lshrrev_b32_e32 v202, 3, v222
	v_lshrrev_b32_e32 v203, 4, v222
	v_xor_b32_e32 v203, v203, v222
	v_and_b32_e32 v203, 7, v203
	v_lshlrev_b32_e32 v210, 4, v203
	v_mov_b32_e32 v200, s46
	v_mov_b32_e32 v201, s47
	v_add_u32_e32 v204, s28, v202
	v_mov_b32_e32 v205, 0
	v_cmp_gt_u32_e32 vcc, s6, v204
	v_lshlrev_b64 v[196:197], 11, v[204:205]
	v_lshl_add_u64 v[196:197], s[64:65], 0, v[196:197]
	v_cndmask_b32_e32 v196, v200, v196, vcc
	v_cndmask_b32_e32 v197, v201, v197, vcc
	v_lshl_add_u64 v[218:219], v[196:197], 0, v[210:211]
	v_add_u32_e32 v204, 64, v204
	v_cmp_gt_u32_e32 vcc, s6, v204
	v_lshlrev_b64 v[196:197], 11, v[204:205]
	v_lshl_add_u64 v[196:197], s[64:65], 0, v[196:197]
	v_cndmask_b32_e32 v196, v200, v196, vcc
	v_cndmask_b32_e32 v197, v201, v197, vcc
	v_lshl_add_u64 v[220:221], v[196:197], 0, v[210:211]
	v_add_u32_e32 v204, 64, v204
	v_cmp_gt_u32_e32 vcc, s6, v204
	v_lshlrev_b64 v[196:197], 11, v[204:205]
	v_lshl_add_u64 v[196:197], s[64:65], 0, v[196:197]
	v_cndmask_b32_e32 v196, v200, v196, vcc
	v_cndmask_b32_e32 v197, v201, v197, vcc
	v_lshl_add_u64 v[224:225], v[196:197], 0, v[210:211]
	v_add_u32_e32 v204, 64, v204
	v_cmp_gt_u32_e32 vcc, s6, v204
	v_lshlrev_b64 v[196:197], 11, v[204:205]
	v_lshl_add_u64 v[196:197], s[64:65], 0, v[196:197]
	v_cndmask_b32_e32 v196, v200, v196, vcc
	v_cndmask_b32_e32 v197, v201, v197, vcc
	v_lshl_add_u64 v[226:227], v[196:197], 0, v[210:211]
	s_lshl_b32 s2, s18, 19
	s_add_u32 s2, s55, s2
	s_addc_u32 s3, s48, 0
	v_lshlrev_b32_e32 v196, 11, v202
	v_add_u32_e32 v196, v196, v210
	v_mov_b32_e32 v197, 0
	v_lshl_add_u64 v[228:229], v[196:197], 0, s[2:3]
	v_readfirstlane_b32 s19, v222
	s_nop 3
	s_lshr_b32 s29, s19, 8
	s_lshr_b32 s19, s19, 6
	s_lshl_b32 s19, s19, 10
	s_barrier
	s_mov_b32 s20, 0
	s_mov_b32 s21, 0
	s_mov_b32 s23, 0
	s_mov_b32 m0, s19
	v_lshl_add_u64 v[196:197], v[218:219], 0, s[20:21]
	global_load_lds_dwordx4 v[196:197], off
	s_add_i32 m0, s19, 0x2000
	v_lshl_add_u64 v[198:199], v[220:221], 0, s[20:21]
	global_load_lds_dwordx4 v[198:199], off
	s_add_i32 m0, s19, 0x4000
	v_lshl_add_u64 v[196:197], v[224:225], 0, s[20:21]
	global_load_lds_dwordx4 v[196:197], off
	s_add_i32 m0, s19, 0x6000
	v_lshl_add_u64 v[198:199], v[226:227], 0, s[20:21]
	global_load_lds_dwordx4 v[198:199], off
	s_add_i32 m0, s19, 0x8000
	v_lshl_add_u64 v[196:197], v[228:229], 0, s[20:21]
	global_load_lds_dwordx4 v[196:197], off
	s_add_u32 s22, s20, 0x20000
	s_add_i32 m0, s19, 0xa000
	v_lshl_add_u64 v[198:199], v[228:229], 0, s[22:23]
	global_load_lds_dwordx4 v[198:199], off
	s_add_u32 s22, s20, 0x40000
	s_add_i32 m0, s19, 0xc000
	v_lshl_add_u64 v[196:197], v[228:229], 0, s[22:23]
	global_load_lds_dwordx4 v[196:197], off
	s_add_u32 s22, s20, 0x60000
	s_add_i32 m0, s19, 0xe000
	v_lshl_add_u64 v[198:199], v[228:229], 0, s[22:23]
	global_load_lds_dwordx4 v[198:199], off
	s_waitcnt vmcnt(0)
.Lp4_cont:
	v_and_b32_e32 v196, 15, v222
	v_bfe_u32 v197, v222, 4, 2
	v_bfe_u32 v198, v196, 1, 3
	v_xor_b32_e32 v197, v197, v198
	v_lshlrev_b32_e32 v197, 4, v197
	v_lshrrev_b32_e32 v198, 8, v222
	v_lshl_or_b32 v198, v198, 7, v196
	v_lshl_or_b32 v188, v198, 7, v197
	v_xor_b32_e32 v189, 64, v188
	v_bfe_u32 v198, v222, 6, 2
	v_lshl_or_b32 v198, v198, 6, v196
	v_lshl_or_b32 v190, v198, 7, v197
	v_xor_b32_e32 v191, 64, v190
	v_add_u32_e32 v192, 0x10000, v188
	v_add_u32_e32 v193, 0x10000, v189
	v_add_u32_e32 v194, 0x10000, v190
	v_add_u32_e32 v195, 0x10000, v191
	v_readfirstlane_b32 s19, v222
	s_nop 3
	s_lshr_b32 s29, s19, 8
	s_lshr_b32 s19, s19, 6
	s_lshl_b32 s19, s19, 10
	s_mov_b32 s20, 0
	s_mov_b32 s21, 0
	s_mov_b32 s23, 0
	s_barrier
	s_add_u32 s22, s20, 0x80
	s_add_i32 m0, s19, 0x10000
	v_lshl_add_u64 v[196:197], v[218:219], 0, s[22:23]
	global_load_lds_dwordx4 v[196:197], off
	s_add_u32 s22, s20, 0x80
	s_add_i32 m0, s19, 0x18000
	v_lshl_add_u64 v[198:199], v[228:229], 0, s[22:23]
	global_load_lds_dwordx4 v[198:199], off
	s_waitcnt vmcnt(18)
	s_barrier
	s_cmp_eq_u32 s29, 0
	s_cbranch_scc1 .Lp4_skew0
	s_barrier
.Lp4_skew0:
	ds_read_b128 v[130:133], v188 offset:0
	ds_read_b128 v[134:137], v188 offset:2048
	ds_read_b128 v[138:141], v188 offset:4096
	ds_read_b128 v[142:145], v188 offset:6144
	ds_read_b128 v[162:165], v190 offset:32768
	ds_read_b128 v[166:169], v190 offset:34816
	ds_read_b128 v[170:173], v190 offset:36864
	ds_read_b128 v[174:177], v190 offset:38912
	s_add_u32 s22, s20, 0x80
	s_add_i32 m0, s19, 0x14000
	v_lshl_add_u64 v[196:197], v[224:225], 0, s[22:23]
	global_load_lds_dwordx4 v[196:197], off
	s_add_u32 s22, s20, 0x20080
	s_add_i32 m0, s19, 0x1a000
	v_lshl_add_u64 v[198:199], v[228:229], 0, s[22:23]
	global_load_lds_dwordx4 v[198:199], off
	s_waitcnt lgkmcnt(0)
	s_barrier
	v_mfma_f32_16x16x32_f16 v[126:129], v[162:165], v[130:133], 0
	v_mfma_f32_16x16x32_f16 v[122:125], v[166:169], v[130:133], 0
	v_mfma_f32_16x16x32_f16 v[118:121], v[170:173], v[130:133], 0
	v_mfma_f32_16x16x32_f16 v[114:117], v[174:177], v[130:133], 0
	v_mfma_f32_16x16x32_f16 v[110:113], v[162:165], v[134:137], 0
	v_mfma_f32_16x16x32_f16 v[106:109], v[166:169], v[134:137], 0
	v_mfma_f32_16x16x32_f16 v[102:105], v[170:173], v[134:137], 0
	v_mfma_f32_16x16x32_f16 v[98:101], v[174:177], v[134:137], 0
	v_mfma_f32_16x16x32_f16 v[94:97], v[162:165], v[138:141], 0
	v_mfma_f32_16x16x32_f16 v[90:93], v[166:169], v[138:141], 0
	v_mfma_f32_16x16x32_f16 v[86:89], v[170:173], v[138:141], 0
	v_mfma_f32_16x16x32_f16 v[82:85], v[174:177], v[138:141], 0
	v_mfma_f32_16x16x32_f16 v[78:81], v[162:165], v[142:145], 0
	v_mfma_f32_16x16x32_f16 v[74:77], v[166:169], v[142:145], 0
	v_mfma_f32_16x16x32_f16 v[70:73], v[170:173], v[142:145], 0
	v_mfma_f32_16x16x32_f16 v[66:69], v[174:177], v[142:145], 0
	s_barrier
	ds_read_b128 v[146:149], v188 offset:8192
	ds_read_b128 v[150:153], v188 offset:10240
	ds_read_b128 v[154:157], v188 offset:12288
	ds_read_b128 v[158:161], v188 offset:14336
	s_add_u32 s22, s20, 0x40080
	s_add_i32 m0, s19, 0x1c000
	v_lshl_add_u64 v[196:197], v[228:229], 0, s[22:23]
	global_load_lds_dwordx4 v[196:197], off
	s_add_u32 s22, s20, 0x60080
	s_add_i32 m0, s19, 0x1e000
	v_lshl_add_u64 v[198:199], v[228:229], 0, s[22:23]
	global_load_lds_dwordx4 v[198:199], off
	s_waitcnt lgkmcnt(0)
	s_barrier
	v_mfma_f32_16x16x32_f16 v[62:65], v[162:165], v[146:149], 0
	v_mfma_f32_16x16x32_f16 v[58:61], v[166:169], v[146:149], 0
	v_mfma_f32_16x16x32_f16 v[54:57], v[170:173], v[146:149], 0
	v_mfma_f32_16x16x32_f16 v[50:53], v[174:177], v[146:149], 0
	v_mfma_f32_16x16x32_f16 v[46:49], v[162:165], v[150:153], 0
	v_mfma_f32_16x16x32_f16 v[42:45], v[166:169], v[150:153], 0
	v_mfma_f32_16x16x32_f16 v[38:41], v[170:173], v[150:153], 0
	v_mfma_f32_16x16x32_f16 v[34:37], v[174:177], v[150:153], 0
	v_mfma_f32_16x16x32_f16 v[30:33], v[162:165], v[154:157], 0
	v_mfma_f32_16x16x32_f16 v[26:29], v[166:169], v[154:157], 0
	v_mfma_f32_16x16x32_f16 v[22:25], v[170:173], v[154:157], 0
	v_mfma_f32_16x16x32_f16 v[18:21], v[174:177], v[154:157], 0
	v_mfma_f32_16x16x32_f16 v[14:17], v[162:165], v[158:161], 0
	v_mfma_f32_16x16x32_f16 v[10:13], v[166:169], v[158:161], 0
	v_mfma_f32_16x16x32_f16 v[6:9], v[170:173], v[158:161], 0
	v_mfma_f32_16x16x32_f16 v[2:5], v[174:177], v[158:161], 0
	s_barrier
	ds_read_b128 v[130:133], v189 offset:0
	ds_read_b128 v[134:137], v189 offset:2048
	ds_read_b128 v[138:141], v189 offset:4096
	ds_read_b128 v[142:145], v189 offset:6144
	ds_read_b128 v[162:165], v191 offset:32768
	ds_read_b128 v[166:169], v191 offset:34816
	ds_read_b128 v[170:173], v191 offset:36864
	ds_read_b128 v[174:177], v191 offset:38912
	s_add_u32 s22, s20, 0x80
	s_add_i32 m0, s19, 0x12000
	v_lshl_add_u64 v[196:197], v[220:221], 0, s[22:23]
	global_load_lds_dwordx4 v[196:197], off
	s_add_u32 s22, s20, 0x80
	s_add_i32 m0, s19, 0x16000
	v_lshl_add_u64 v[198:199], v[226:227], 0, s[22:23]
	global_load_lds_dwordx4 v[198:199], off
	s_waitcnt lgkmcnt(0)
	s_barrier
	v_mfma_f32_16x16x32_f16 v[126:129], v[162:165], v[130:133], v[126:129]
	v_mfma_f32_16x16x32_f16 v[122:125], v[166:169], v[130:133], v[122:125]
	v_mfma_f32_16x16x32_f16 v[118:121], v[170:173], v[130:133], v[118:121]
	v_mfma_f32_16x16x32_f16 v[114:117], v[174:177], v[130:133], v[114:117]
	v_mfma_f32_16x16x32_f16 v[110:113], v[162:165], v[134:137], v[110:113]
	v_mfma_f32_16x16x32_f16 v[106:109], v[166:169], v[134:137], v[106:109]
	v_mfma_f32_16x16x32_f16 v[102:105], v[170:173], v[134:137], v[102:105]
	v_mfma_f32_16x16x32_f16 v[98:101], v[174:177], v[134:137], v[98:101]
	v_mfma_f32_16x16x32_f16 v[94:97], v[162:165], v[138:141], v[94:97]
	v_mfma_f32_16x16x32_f16 v[90:93], v[166:169], v[138:141], v[90:93]
	v_mfma_f32_16x16x32_f16 v[86:89], v[170:173], v[138:141], v[86:89]
	v_mfma_f32_16x16x32_f16 v[82:85], v[174:177], v[138:141], v[82:85]
	v_mfma_f32_16x16x32_f16 v[78:81], v[162:165], v[142:145], v[78:81]
	v_mfma_f32_16x16x32_f16 v[74:77], v[166:169], v[142:145], v[74:77]
	v_mfma_f32_16x16x32_f16 v[70:73], v[170:173], v[142:145], v[70:73]
	v_mfma_f32_16x16x32_f16 v[66:69], v[174:177], v[142:145], v[66:69]
	s_barrier
	ds_read_b128 v[146:149], v189 offset:8192
	ds_read_b128 v[150:153], v189 offset:10240
	ds_read_b128 v[154:157], v189 offset:12288
	ds_read_b128 v[158:161], v189 offset:14336
	s_add_u32 s22, s20, 0x100
	s_mov_b32 m0, s19
	v_lshl_add_u64 v[196:197], v[218:219], 0, s[22:23]
	global_load_lds_dwordx4 v[196:197], off
	s_add_u32 s22, s20, 0x100
	s_add_i32 m0, s19, 0x8000
	v_lshl_add_u64 v[198:199], v[228:229], 0, s[22:23]
	global_load_lds_dwordx4 v[198:199], off
	s_waitcnt vmcnt(4) lgkmcnt(0)
	s_barrier
	v_mfma_f32_16x16x32_f16 v[62:65], v[162:165], v[146:149], v[62:65]
	v_mfma_f32_16x16x32_f16 v[58:61], v[166:169], v[146:149], v[58:61]
	v_mfma_f32_16x16x32_f16 v[54:57], v[170:173], v[146:149], v[54:57]
	v_mfma_f32_16x16x32_f16 v[50:53], v[174:177], v[146:149], v[50:53]
	v_mfma_f32_16x16x32_f16 v[46:49], v[162:165], v[150:153], v[46:49]
	v_mfma_f32_16x16x32_f16 v[42:45], v[166:169], v[150:153], v[42:45]
	v_mfma_f32_16x16x32_f16 v[38:41], v[170:173], v[150:153], v[38:41]
	v_mfma_f32_16x16x32_f16 v[34:37], v[174:177], v[150:153], v[34:37]
	v_mfma_f32_16x16x32_f16 v[30:33], v[162:165], v[154:157], v[30:33]
	v_mfma_f32_16x16x32_f16 v[26:29], v[166:169], v[154:157], v[26:29]
	v_mfma_f32_16x16x32_f16 v[22:25], v[170:173], v[154:157], v[22:25]
	v_mfma_f32_16x16x32_f16 v[18:21], v[174:177], v[154:157], v[18:21]
	v_mfma_f32_16x16x32_f16 v[14:17], v[162:165], v[158:161], v[14:17]
	v_mfma_f32_16x16x32_f16 v[10:13], v[166:169], v[158:161], v[10:13]
	v_mfma_f32_16x16x32_f16 v[6:9], v[170:173], v[158:161], v[6:9]
	v_mfma_f32_16x16x32_f16 v[2:5], v[174:177], v[158:161], v[2:5]
	s_barrier
	s_add_u32 s20, s20, 0x80
	ds_read_b128 v[130:133], v192 offset:0
	ds_read_b128 v[134:137], v192 offset:2048
	ds_read_b128 v[138:141], v192 offset:4096
	ds_read_b128 v[142:145], v192 offset:6144
	ds_read_b128 v[162:165], v194 offset:32768
	ds_read_b128 v[166:169], v194 offset:34816
	ds_read_b128 v[170:173], v194 offset:36864
	ds_read_b128 v[174:177], v194 offset:38912
	s_add_u32 s22, s20, 0x80
	s_add_i32 m0, s19, 0x4000
	v_lshl_add_u64 v[196:197], v[224:225], 0, s[22:23]
	global_load_lds_dwordx4 v[196:197], off
	s_add_u32 s22, s20, 0x20080
	s_add_i32 m0, s19, 0xa000
	v_lshl_add_u64 v[198:199], v[228:229], 0, s[22:23]
	global_load_lds_dwordx4 v[198:199], off
	s_waitcnt vmcnt(4) lgkmcnt(0)
	s_barrier
	v_mfma_f32_16x16x32_f16 v[126:129], v[162:165], v[130:133], v[126:129]
	v_mfma_f32_16x16x32_f16 v[122:125], v[166:169], v[130:133], v[122:125]
	v_mfma_f32_16x16x32_f16 v[118:121], v[170:173], v[130:133], v[118:121]
	v_mfma_f32_16x16x32_f16 v[114:117], v[174:177], v[130:133], v[114:117]
	v_mfma_f32_16x16x32_f16 v[110:113], v[162:165], v[134:137], v[110:113]
	v_mfma_f32_16x16x32_f16 v[106:109], v[166:169], v[134:137], v[106:109]
	v_mfma_f32_16x16x32_f16 v[102:105], v[170:173], v[134:137], v[102:105]
	v_mfma_f32_16x16x32_f16 v[98:101], v[174:177], v[134:137], v[98:101]
	v_mfma_f32_16x16x32_f16 v[94:97], v[162:165], v[138:141], v[94:97]
	v_mfma_f32_16x16x32_f16 v[90:93], v[166:169], v[138:141], v[90:93]
	v_mfma_f32_16x16x32_f16 v[86:89], v[170:173], v[138:141], v[86:89]
	v_mfma_f32_16x16x32_f16 v[82:85], v[174:177], v[138:141], v[82:85]
	v_mfma_f32_16x16x32_f16 v[78:81], v[162:165], v[142:145], v[78:81]
	v_mfma_f32_16x16x32_f16 v[74:77], v[166:169], v[142:145], v[74:77]
	v_mfma_f32_16x16x32_f16 v[70:73], v[170:173], v[142:145], v[70:73]
	v_mfma_f32_16x16x32_f16 v[66:69], v[174:177], v[142:145], v[66:69]
	s_barrier
	ds_read_b128 v[146:149], v192 offset:8192
	ds_read_b128 v[150:153], v192 offset:10240
	ds_read_b128 v[154:157], v192 offset:12288
	ds_read_b128 v[158:161], v192 offset:14336
	s_add_u32 s22, s20, 0x40080
	s_add_i32 m0, s19, 0xc000
	v_lshl_add_u64 v[196:197], v[228:229], 0, s[22:23]
	global_load_lds_dwordx4 v[196:197], off
	s_add_u32 s22, s20, 0x60080
	s_add_i32 m0, s19, 0xe000
	v_lshl_add_u64 v[198:199], v[228:229], 0, s[22:23]
	global_load_lds_dwordx4 v[198:199], off
	s_waitcnt lgkmcnt(0)
	s_barrier
	v_mfma_f32_16x16x32_f16 v[62:65], v[162:165], v[146:149], v[62:65]
	v_mfma_f32_16x16x32_f16 v[58:61], v[166:169], v[146:149], v[58:61]
	v_mfma_f32_16x16x32_f16 v[54:57], v[170:173], v[146:149], v[54:57]
	v_mfma_f32_16x16x32_f16 v[50:53], v[174:177], v[146:149], v[50:53]
	v_mfma_f32_16x16x32_f16 v[46:49], v[162:165], v[150:153], v[46:49]
	v_mfma_f32_16x16x32_f16 v[42:45], v[166:169], v[150:153], v[42:45]
	v_mfma_f32_16x16x32_f16 v[38:41], v[170:173], v[150:153], v[38:41]
	v_mfma_f32_16x16x32_f16 v[34:37], v[174:177], v[150:153], v[34:37]
	v_mfma_f32_16x16x32_f16 v[30:33], v[162:165], v[154:157], v[30:33]
	v_mfma_f32_16x16x32_f16 v[26:29], v[166:169], v[154:157], v[26:29]
	v_mfma_f32_16x16x32_f16 v[22:25], v[170:173], v[154:157], v[22:25]
	v_mfma_f32_16x16x32_f16 v[18:21], v[174:177], v[154:157], v[18:21]
	v_mfma_f32_16x16x32_f16 v[14:17], v[162:165], v[158:161], v[14:17]
	v_mfma_f32_16x16x32_f16 v[10:13], v[166:169], v[158:161], v[10:13]
	v_mfma_f32_16x16x32_f16 v[6:9], v[170:173], v[158:161], v[6:9]
	v_mfma_f32_16x16x32_f16 v[2:5], v[174:177], v[158:161], v[2:5]
	s_barrier
	ds_read_b128 v[130:133], v193 offset:0
	ds_read_b128 v[134:137], v193 offset:2048
	ds_read_b128 v[138:141], v193 offset:4096
	ds_read_b128 v[142:145], v193 offset:6144
	ds_read_b128 v[162:165], v195 offset:32768
	ds_read_b128 v[166:169], v195 offset:34816
	ds_read_b128 v[170:173], v195 offset:36864
	ds_read_b128 v[174:177], v195 offset:38912
	s_add_u32 s22, s20, 0x80
	s_add_i32 m0, s19, 0x2000
	v_lshl_add_u64 v[196:197], v[220:221], 0, s[22:23]
	global_load_lds_dwordx4 v[196:197], off
	s_add_u32 s22, s20, 0x80
	s_add_i32 m0, s19, 0x6000
	v_lshl_add_u64 v[198:199], v[226:227], 0, s[22:23]
	global_load_lds_dwordx4 v[198:199], off
	s_waitcnt lgkmcnt(0)
	s_barrier
	v_mfma_f32_16x16x32_f16 v[126:129], v[162:165], v[130:133], v[126:129]
	v_mfma_f32_16x16x32_f16 v[122:125], v[166:169], v[130:133], v[122:125]
	v_mfma_f32_16x16x32_f16 v[118:121], v[170:173], v[130:133], v[118:121]
	v_mfma_f32_16x16x32_f16 v[114:117], v[174:177], v[130:133], v[114:117]
	v_mfma_f32_16x16x32_f16 v[110:113], v[162:165], v[134:137], v[110:113]
	v_mfma_f32_16x16x32_f16 v[106:109], v[166:169], v[134:137], v[106:109]
	v_mfma_f32_16x16x32_f16 v[102:105], v[170:173], v[134:137], v[102:105]
	v_mfma_f32_16x16x32_f16 v[98:101], v[174:177], v[134:137], v[98:101]
	v_mfma_f32_16x16x32_f16 v[94:97], v[162:165], v[138:141], v[94:97]
	v_mfma_f32_16x16x32_f16 v[90:93], v[166:169], v[138:141], v[90:93]
	v_mfma_f32_16x16x32_f16 v[86:89], v[170:173], v[138:141], v[86:89]
	v_mfma_f32_16x16x32_f16 v[82:85], v[174:177], v[138:141], v[82:85]
	v_mfma_f32_16x16x32_f16 v[78:81], v[162:165], v[142:145], v[78:81]
	v_mfma_f32_16x16x32_f16 v[74:77], v[166:169], v[142:145], v[74:77]
	v_mfma_f32_16x16x32_f16 v[70:73], v[170:173], v[142:145], v[70:73]
	v_mfma_f32_16x16x32_f16 v[66:69], v[174:177], v[142:145], v[66:69]
	s_barrier
	ds_read_b128 v[146:149], v193 offset:8192
	ds_read_b128 v[150:153], v193 offset:10240
	ds_read_b128 v[154:157], v193 offset:12288
	ds_read_b128 v[158:161], v193 offset:14336
	s_add_u32 s22, s20, 0x100
	s_add_i32 m0, s19, 0x10000
	v_lshl_add_u64 v[196:197], v[218:219], 0, s[22:23]
	global_load_lds_dwordx4 v[196:197], off
	s_add_u32 s22, s20, 0x100
	s_add_i32 m0, s19, 0x18000
	v_lshl_add_u64 v[198:199], v[228:229], 0, s[22:23]
	global_load_lds_dwordx4 v[198:199], off
	s_waitcnt vmcnt(4) lgkmcnt(0)
	s_barrier
	v_mfma_f32_16x16x32_f16 v[62:65], v[162:165], v[146:149], v[62:65]
	v_mfma_f32_16x16x32_f16 v[58:61], v[166:169], v[146:149], v[58:61]
	v_mfma_f32_16x16x32_f16 v[54:57], v[170:173], v[146:149], v[54:57]
	v_mfma_f32_16x16x32_f16 v[50:53], v[174:177], v[146:149], v[50:53]
	v_mfma_f32_16x16x32_f16 v[46:49], v[162:165], v[150:153], v[46:49]
	v_mfma_f32_16x16x32_f16 v[42:45], v[166:169], v[150:153], v[42:45]
	v_mfma_f32_16x16x32_f16 v[38:41], v[170:173], v[150:153], v[38:41]
	v_mfma_f32_16x16x32_f16 v[34:37], v[174:177], v[150:153], v[34:37]
	v_mfma_f32_16x16x32_f16 v[30:33], v[162:165], v[154:157], v[30:33]
	v_mfma_f32_16x16x32_f16 v[26:29], v[166:169], v[154:157], v[26:29]
	v_mfma_f32_16x16x32_f16 v[22:25], v[170:173], v[154:157], v[22:25]
	v_mfma_f32_16x16x32_f16 v[18:21], v[174:177], v[154:157], v[18:21]
	v_mfma_f32_16x16x32_f16 v[14:17], v[162:165], v[158:161], v[14:17]
	v_mfma_f32_16x16x32_f16 v[10:13], v[166:169], v[158:161], v[10:13]
	v_mfma_f32_16x16x32_f16 v[6:9], v[170:173], v[158:161], v[6:9]
	v_mfma_f32_16x16x32_f16 v[2:5], v[174:177], v[158:161], v[2:5]
	s_barrier
	s_add_u32 s20, s20, 0x80
	s_movk_i32 s33, 6
.Lp4_loop:
	ds_read_b128 v[130:133], v188 offset:0
	ds_read_b128 v[134:137], v188 offset:2048
	ds_read_b128 v[138:141], v188 offset:4096
	ds_read_b128 v[142:145], v188 offset:6144
	ds_read_b128 v[162:165], v190 offset:32768
	ds_read_b128 v[166:169], v190 offset:34816
	ds_read_b128 v[170:173], v190 offset:36864
	ds_read_b128 v[174:177], v190 offset:38912
	s_add_u32 s22, s20, 0x80
	s_add_i32 m0, s19, 0x14000
	v_lshl_add_u64 v[196:197], v[224:225], 0, s[22:23]
	global_load_lds_dwordx4 v[196:197], off
	s_add_u32 s22, s20, 0x20080
	s_add_i32 m0, s19, 0x1a000
	v_lshl_add_u64 v[198:199], v[228:229], 0, s[22:23]
	global_load_lds_dwordx4 v[198:199], off
	s_waitcnt vmcnt(4) lgkmcnt(0)
	s_barrier
	v_mfma_f32_16x16x32_f16 v[126:129], v[162:165], v[130:133], v[126:129]
	v_mfma_f32_16x16x32_f16 v[122:125], v[166:169], v[130:133], v[122:125]
	v_mfma_f32_16x16x32_f16 v[118:121], v[170:173], v[130:133], v[118:121]
	v_mfma_f32_16x16x32_f16 v[114:117], v[174:177], v[130:133], v[114:117]
	v_mfma_f32_16x16x32_f16 v[110:113], v[162:165], v[134:137], v[110:113]
	v_mfma_f32_16x16x32_f16 v[106:109], v[166:169], v[134:137], v[106:109]
	v_mfma_f32_16x16x32_f16 v[102:105], v[170:173], v[134:137], v[102:105]
	v_mfma_f32_16x16x32_f16 v[98:101], v[174:177], v[134:137], v[98:101]
	v_mfma_f32_16x16x32_f16 v[94:97], v[162:165], v[138:141], v[94:97]
	v_mfma_f32_16x16x32_f16 v[90:93], v[166:169], v[138:141], v[90:93]
	v_mfma_f32_16x16x32_f16 v[86:89], v[170:173], v[138:141], v[86:89]
	v_mfma_f32_16x16x32_f16 v[82:85], v[174:177], v[138:141], v[82:85]
	v_mfma_f32_16x16x32_f16 v[78:81], v[162:165], v[142:145], v[78:81]
	v_mfma_f32_16x16x32_f16 v[74:77], v[166:169], v[142:145], v[74:77]
	v_mfma_f32_16x16x32_f16 v[70:73], v[170:173], v[142:145], v[70:73]
	v_mfma_f32_16x16x32_f16 v[66:69], v[174:177], v[142:145], v[66:69]
	s_barrier
	ds_read_b128 v[146:149], v188 offset:8192
	ds_read_b128 v[150:153], v188 offset:10240
	ds_read_b128 v[154:157], v188 offset:12288
	ds_read_b128 v[158:161], v188 offset:14336
	s_add_u32 s22, s20, 0x40080
	s_add_i32 m0, s19, 0x1c000
	v_lshl_add_u64 v[196:197], v[228:229], 0, s[22:23]
	global_load_lds_dwordx4 v[196:197], off
	s_add_u32 s22, s20, 0x60080
	s_add_i32 m0, s19, 0x1e000
	v_lshl_add_u64 v[198:199], v[228:229], 0, s[22:23]
	global_load_lds_dwordx4 v[198:199], off
	s_waitcnt lgkmcnt(0)
	s_barrier
	v_mfma_f32_16x16x32_f16 v[62:65], v[162:165], v[146:149], v[62:65]
	v_mfma_f32_16x16x32_f16 v[58:61], v[166:169], v[146:149], v[58:61]
	v_mfma_f32_16x16x32_f16 v[54:57], v[170:173], v[146:149], v[54:57]
	v_mfma_f32_16x16x32_f16 v[50:53], v[174:177], v[146:149], v[50:53]
	v_mfma_f32_16x16x32_f16 v[46:49], v[162:165], v[150:153], v[46:49]
	v_mfma_f32_16x16x32_f16 v[42:45], v[166:169], v[150:153], v[42:45]
	v_mfma_f32_16x16x32_f16 v[38:41], v[170:173], v[150:153], v[38:41]
	v_mfma_f32_16x16x32_f16 v[34:37], v[174:177], v[150:153], v[34:37]
	v_mfma_f32_16x16x32_f16 v[30:33], v[162:165], v[154:157], v[30:33]
	v_mfma_f32_16x16x32_f16 v[26:29], v[166:169], v[154:157], v[26:29]
	v_mfma_f32_16x16x32_f16 v[22:25], v[170:173], v[154:157], v[22:25]
	v_mfma_f32_16x16x32_f16 v[18:21], v[174:177], v[154:157], v[18:21]
	v_mfma_f32_16x16x32_f16 v[14:17], v[162:165], v[158:161], v[14:17]
	v_mfma_f32_16x16x32_f16 v[10:13], v[166:169], v[158:161], v[10:13]
	v_mfma_f32_16x16x32_f16 v[6:9], v[170:173], v[158:161], v[6:9]
	v_mfma_f32_16x16x32_f16 v[2:5], v[174:177], v[158:161], v[2:5]
	s_barrier
	ds_read_b128 v[130:133], v189 offset:0
	ds_read_b128 v[134:137], v189 offset:2048
	ds_read_b128 v[138:141], v189 offset:4096
	ds_read_b128 v[142:145], v189 offset:6144
	ds_read_b128 v[162:165], v191 offset:32768
	ds_read_b128 v[166:169], v191 offset:34816
	ds_read_b128 v[170:173], v191 offset:36864
	ds_read_b128 v[174:177], v191 offset:38912
	s_add_u32 s22, s20, 0x80
	s_add_i32 m0, s19, 0x12000
	v_lshl_add_u64 v[196:197], v[220:221], 0, s[22:23]
	global_load_lds_dwordx4 v[196:197], off
	s_add_u32 s22, s20, 0x80
	s_add_i32 m0, s19, 0x16000
	v_lshl_add_u64 v[198:199], v[226:227], 0, s[22:23]
	global_load_lds_dwordx4 v[198:199], off
	s_waitcnt lgkmcnt(0)
	s_barrier
	v_mfma_f32_16x16x32_f16 v[126:129], v[162:165], v[130:133], v[126:129]
	v_mfma_f32_16x16x32_f16 v[122:125], v[166:169], v[130:133], v[122:125]
	v_mfma_f32_16x16x32_f16 v[118:121], v[170:173], v[130:133], v[118:121]
	v_mfma_f32_16x16x32_f16 v[114:117], v[174:177], v[130:133], v[114:117]
	v_mfma_f32_16x16x32_f16 v[110:113], v[162:165], v[134:137], v[110:113]
	v_mfma_f32_16x16x32_f16 v[106:109], v[166:169], v[134:137], v[106:109]
	v_mfma_f32_16x16x32_f16 v[102:105], v[170:173], v[134:137], v[102:105]
	v_mfma_f32_16x16x32_f16 v[98:101], v[174:177], v[134:137], v[98:101]
	v_mfma_f32_16x16x32_f16 v[94:97], v[162:165], v[138:141], v[94:97]
	v_mfma_f32_16x16x32_f16 v[90:93], v[166:169], v[138:141], v[90:93]
	v_mfma_f32_16x16x32_f16 v[86:89], v[170:173], v[138:141], v[86:89]
	v_mfma_f32_16x16x32_f16 v[82:85], v[174:177], v[138:141], v[82:85]
	v_mfma_f32_16x16x32_f16 v[78:81], v[162:165], v[142:145], v[78:81]
	v_mfma_f32_16x16x32_f16 v[74:77], v[166:169], v[142:145], v[74:77]
	v_mfma_f32_16x16x32_f16 v[70:73], v[170:173], v[142:145], v[70:73]
	v_mfma_f32_16x16x32_f16 v[66:69], v[174:177], v[142:145], v[66:69]
	s_barrier
	ds_read_b128 v[146:149], v189 offset:8192
	ds_read_b128 v[150:153], v189 offset:10240
	ds_read_b128 v[154:157], v189 offset:12288
	ds_read_b128 v[158:161], v189 offset:14336
	s_add_u32 s22, s20, 0x100
	s_mov_b32 m0, s19
	v_lshl_add_u64 v[196:197], v[218:219], 0, s[22:23]
	global_load_lds_dwordx4 v[196:197], off
	s_add_u32 s22, s20, 0x100
	s_add_i32 m0, s19, 0x8000
	v_lshl_add_u64 v[198:199], v[228:229], 0, s[22:23]
	global_load_lds_dwordx4 v[198:199], off
	s_waitcnt vmcnt(4) lgkmcnt(0)
	s_barrier
	v_mfma_f32_16x16x32_f16 v[62:65], v[162:165], v[146:149], v[62:65]
	v_mfma_f32_16x16x32_f16 v[58:61], v[166:169], v[146:149], v[58:61]
	v_mfma_f32_16x16x32_f16 v[54:57], v[170:173], v[146:149], v[54:57]
	v_mfma_f32_16x16x32_f16 v[50:53], v[174:177], v[146:149], v[50:53]
	v_mfma_f32_16x16x32_f16 v[46:49], v[162:165], v[150:153], v[46:49]
	v_mfma_f32_16x16x32_f16 v[42:45], v[166:169], v[150:153], v[42:45]
	v_mfma_f32_16x16x32_f16 v[38:41], v[170:173], v[150:153], v[38:41]
	v_mfma_f32_16x16x32_f16 v[34:37], v[174:177], v[150:153], v[34:37]
	v_mfma_f32_16x16x32_f16 v[30:33], v[162:165], v[154:157], v[30:33]
	v_mfma_f32_16x16x32_f16 v[26:29], v[166:169], v[154:157], v[26:29]
	v_mfma_f32_16x16x32_f16 v[22:25], v[170:173], v[154:157], v[22:25]
	v_mfma_f32_16x16x32_f16 v[18:21], v[174:177], v[154:157], v[18:21]
	v_mfma_f32_16x16x32_f16 v[14:17], v[162:165], v[158:161], v[14:17]
	v_mfma_f32_16x16x32_f16 v[10:13], v[166:169], v[158:161], v[10:13]
	v_mfma_f32_16x16x32_f16 v[6:9], v[170:173], v[158:161], v[6:9]
	v_mfma_f32_16x16x32_f16 v[2:5], v[174:177], v[158:161], v[2:5]
	s_barrier
	s_add_u32 s20, s20, 0x80
	ds_read_b128 v[130:133], v192 offset:0
	ds_read_b128 v[134:137], v192 offset:2048
	ds_read_b128 v[138:141], v192 offset:4096
	ds_read_b128 v[142:145], v192 offset:6144
	ds_read_b128 v[162:165], v194 offset:32768
	ds_read_b128 v[166:169], v194 offset:34816
	ds_read_b128 v[170:173], v194 offset:36864
	ds_read_b128 v[174:177], v194 offset:38912
	s_add_u32 s22, s20, 0x80
	s_add_i32 m0, s19, 0x4000
	v_lshl_add_u64 v[196:197], v[224:225], 0, s[22:23]
	global_load_lds_dwordx4 v[196:197], off
	s_add_u32 s22, s20, 0x20080
	s_add_i32 m0, s19, 0xa000
	v_lshl_add_u64 v[198:199], v[228:229], 0, s[22:23]
	global_load_lds_dwordx4 v[198:199], off
	s_waitcnt vmcnt(4) lgkmcnt(0)
	s_barrier
	v_mfma_f32_16x16x32_f16 v[126:129], v[162:165], v[130:133], v[126:129]
	v_mfma_f32_16x16x32_f16 v[122:125], v[166:169], v[130:133], v[122:125]
	v_mfma_f32_16x16x32_f16 v[118:121], v[170:173], v[130:133], v[118:121]
	v_mfma_f32_16x16x32_f16 v[114:117], v[174:177], v[130:133], v[114:117]
	v_mfma_f32_16x16x32_f16 v[110:113], v[162:165], v[134:137], v[110:113]
	v_mfma_f32_16x16x32_f16 v[106:109], v[166:169], v[134:137], v[106:109]
	v_mfma_f32_16x16x32_f16 v[102:105], v[170:173], v[134:137], v[102:105]
	v_mfma_f32_16x16x32_f16 v[98:101], v[174:177], v[134:137], v[98:101]
	v_mfma_f32_16x16x32_f16 v[94:97], v[162:165], v[138:141], v[94:97]
	v_mfma_f32_16x16x32_f16 v[90:93], v[166:169], v[138:141], v[90:93]
	v_mfma_f32_16x16x32_f16 v[86:89], v[170:173], v[138:141], v[86:89]
	v_mfma_f32_16x16x32_f16 v[82:85], v[174:177], v[138:141], v[82:85]
	v_mfma_f32_16x16x32_f16 v[78:81], v[162:165], v[142:145], v[78:81]
	v_mfma_f32_16x16x32_f16 v[74:77], v[166:169], v[142:145], v[74:77]
	v_mfma_f32_16x16x32_f16 v[70:73], v[170:173], v[142:145], v[70:73]
	v_mfma_f32_16x16x32_f16 v[66:69], v[174:177], v[142:145], v[66:69]
	s_barrier
	ds_read_b128 v[146:149], v192 offset:8192
	ds_read_b128 v[150:153], v192 offset:10240
	ds_read_b128 v[154:157], v192 offset:12288
	ds_read_b128 v[158:161], v192 offset:14336
	s_add_u32 s22, s20, 0x40080
	s_add_i32 m0, s19, 0xc000
	v_lshl_add_u64 v[196:197], v[228:229], 0, s[22:23]
	global_load_lds_dwordx4 v[196:197], off
	s_add_u32 s22, s20, 0x60080
	s_add_i32 m0, s19, 0xe000
	v_lshl_add_u64 v[198:199], v[228:229], 0, s[22:23]
	global_load_lds_dwordx4 v[198:199], off
	s_waitcnt lgkmcnt(0)
	s_barrier
	v_mfma_f32_16x16x32_f16 v[62:65], v[162:165], v[146:149], v[62:65]
	v_mfma_f32_16x16x32_f16 v[58:61], v[166:169], v[146:149], v[58:61]
	v_mfma_f32_16x16x32_f16 v[54:57], v[170:173], v[146:149], v[54:57]
	v_mfma_f32_16x16x32_f16 v[50:53], v[174:177], v[146:149], v[50:53]
	v_mfma_f32_16x16x32_f16 v[46:49], v[162:165], v[150:153], v[46:49]
	v_mfma_f32_16x16x32_f16 v[42:45], v[166:169], v[150:153], v[42:45]
	v_mfma_f32_16x16x32_f16 v[38:41], v[170:173], v[150:153], v[38:41]
	v_mfma_f32_16x16x32_f16 v[34:37], v[174:177], v[150:153], v[34:37]
	v_mfma_f32_16x16x32_f16 v[30:33], v[162:165], v[154:157], v[30:33]
	v_mfma_f32_16x16x32_f16 v[26:29], v[166:169], v[154:157], v[26:29]
	v_mfma_f32_16x16x32_f16 v[22:25], v[170:173], v[154:157], v[22:25]
	v_mfma_f32_16x16x32_f16 v[18:21], v[174:177], v[154:157], v[18:21]
	v_mfma_f32_16x16x32_f16 v[14:17], v[162:165], v[158:161], v[14:17]
	v_mfma_f32_16x16x32_f16 v[10:13], v[166:169], v[158:161], v[10:13]
	v_mfma_f32_16x16x32_f16 v[6:9], v[170:173], v[158:161], v[6:9]
	v_mfma_f32_16x16x32_f16 v[2:5], v[174:177], v[158:161], v[2:5]
	s_barrier
	ds_read_b128 v[130:133], v193 offset:0
	ds_read_b128 v[134:137], v193 offset:2048
	ds_read_b128 v[138:141], v193 offset:4096
	ds_read_b128 v[142:145], v193 offset:6144
	ds_read_b128 v[162:165], v195 offset:32768
	ds_read_b128 v[166:169], v195 offset:34816
	ds_read_b128 v[170:173], v195 offset:36864
	ds_read_b128 v[174:177], v195 offset:38912
	s_add_u32 s22, s20, 0x80
	s_add_i32 m0, s19, 0x2000
	v_lshl_add_u64 v[196:197], v[220:221], 0, s[22:23]
	global_load_lds_dwordx4 v[196:197], off
	s_add_u32 s22, s20, 0x80
	s_add_i32 m0, s19, 0x6000
	v_lshl_add_u64 v[198:199], v[226:227], 0, s[22:23]
	global_load_lds_dwordx4 v[198:199], off
	s_waitcnt lgkmcnt(0)
	s_barrier
	v_mfma_f32_16x16x32_f16 v[126:129], v[162:165], v[130:133], v[126:129]
	v_mfma_f32_16x16x32_f16 v[122:125], v[166:169], v[130:133], v[122:125]
	v_mfma_f32_16x16x32_f16 v[118:121], v[170:173], v[130:133], v[118:121]
	v_mfma_f32_16x16x32_f16 v[114:117], v[174:177], v[130:133], v[114:117]
	v_mfma_f32_16x16x32_f16 v[110:113], v[162:165], v[134:137], v[110:113]
	v_mfma_f32_16x16x32_f16 v[106:109], v[166:169], v[134:137], v[106:109]
	v_mfma_f32_16x16x32_f16 v[102:105], v[170:173], v[134:137], v[102:105]
	v_mfma_f32_16x16x32_f16 v[98:101], v[174:177], v[134:137], v[98:101]
	v_mfma_f32_16x16x32_f16 v[94:97], v[162:165], v[138:141], v[94:97]
	v_mfma_f32_16x16x32_f16 v[90:93], v[166:169], v[138:141], v[90:93]
	v_mfma_f32_16x16x32_f16 v[86:89], v[170:173], v[138:141], v[86:89]
	v_mfma_f32_16x16x32_f16 v[82:85], v[174:177], v[138:141], v[82:85]
	v_mfma_f32_16x16x32_f16 v[78:81], v[162:165], v[142:145], v[78:81]
	v_mfma_f32_16x16x32_f16 v[74:77], v[166:169], v[142:145], v[74:77]
	v_mfma_f32_16x16x32_f16 v[70:73], v[170:173], v[142:145], v[70:73]
	v_mfma_f32_16x16x32_f16 v[66:69], v[174:177], v[142:145], v[66:69]
	s_barrier
	ds_read_b128 v[146:149], v193 offset:8192
	ds_read_b128 v[150:153], v193 offset:10240
	ds_read_b128 v[154:157], v193 offset:12288
	ds_read_b128 v[158:161], v193 offset:14336
	s_add_u32 s22, s20, 0x100
	s_add_i32 m0, s19, 0x10000
	v_lshl_add_u64 v[196:197], v[218:219], 0, s[22:23]
	global_load_lds_dwordx4 v[196:197], off
	s_add_u32 s22, s20, 0x100
	s_add_i32 m0, s19, 0x18000
	v_lshl_add_u64 v[198:199], v[228:229], 0, s[22:23]
	global_load_lds_dwordx4 v[198:199], off
	s_waitcnt vmcnt(4) lgkmcnt(0)
	s_barrier
	v_mfma_f32_16x16x32_f16 v[62:65], v[162:165], v[146:149], v[62:65]
	v_mfma_f32_16x16x32_f16 v[58:61], v[166:169], v[146:149], v[58:61]
	v_mfma_f32_16x16x32_f16 v[54:57], v[170:173], v[146:149], v[54:57]
	v_mfma_f32_16x16x32_f16 v[50:53], v[174:177], v[146:149], v[50:53]
	v_mfma_f32_16x16x32_f16 v[46:49], v[162:165], v[150:153], v[46:49]
	v_mfma_f32_16x16x32_f16 v[42:45], v[166:169], v[150:153], v[42:45]
	v_mfma_f32_16x16x32_f16 v[38:41], v[170:173], v[150:153], v[38:41]
	v_mfma_f32_16x16x32_f16 v[34:37], v[174:177], v[150:153], v[34:37]
	v_mfma_f32_16x16x32_f16 v[30:33], v[162:165], v[154:157], v[30:33]
	v_mfma_f32_16x16x32_f16 v[26:29], v[166:169], v[154:157], v[26:29]
	v_mfma_f32_16x16x32_f16 v[22:25], v[170:173], v[154:157], v[22:25]
	v_mfma_f32_16x16x32_f16 v[18:21], v[174:177], v[154:157], v[18:21]
	v_mfma_f32_16x16x32_f16 v[14:17], v[162:165], v[158:161], v[14:17]
	v_mfma_f32_16x16x32_f16 v[10:13], v[166:169], v[158:161], v[10:13]
	v_mfma_f32_16x16x32_f16 v[6:9], v[170:173], v[158:161], v[6:9]
	v_mfma_f32_16x16x32_f16 v[2:5], v[174:177], v[158:161], v[2:5]
	s_barrier
	s_add_u32 s20, s20, 0x80
	s_add_i32 s33, s33, -1
	s_cmp_lg_u32 s33, 0
	s_cbranch_scc1 .Lp4_loop
	ds_read_b128 v[130:133], v188 offset:0
	ds_read_b128 v[134:137], v188 offset:2048
	ds_read_b128 v[138:141], v188 offset:4096
	ds_read_b128 v[142:145], v188 offset:6144
	ds_read_b128 v[162:165], v190 offset:32768
	ds_read_b128 v[166:169], v190 offset:34816
	ds_read_b128 v[170:173], v190 offset:36864
	ds_read_b128 v[174:177], v190 offset:38912
	s_add_u32 s22, s20, 0x80
	s_add_i32 m0, s19, 0x14000
	v_lshl_add_u64 v[196:197], v[224:225], 0, s[22:23]
	global_load_lds_dwordx4 v[196:197], off
	s_add_u32 s22, s20, 0x20080
	s_add_i32 m0, s19, 0x1a000
	v_lshl_add_u64 v[198:199], v[228:229], 0, s[22:23]
	global_load_lds_dwordx4 v[198:199], off
	s_waitcnt vmcnt(4) lgkmcnt(0)
	s_barrier
	v_mfma_f32_16x16x32_f16 v[126:129], v[162:165], v[130:133], v[126:129]
	v_mfma_f32_16x16x32_f16 v[122:125], v[166:169], v[130:133], v[122:125]
	v_mfma_f32_16x16x32_f16 v[118:121], v[170:173], v[130:133], v[118:121]
	v_mfma_f32_16x16x32_f16 v[114:117], v[174:177], v[130:133], v[114:117]
	v_mfma_f32_16x16x32_f16 v[110:113], v[162:165], v[134:137], v[110:113]
	v_mfma_f32_16x16x32_f16 v[106:109], v[166:169], v[134:137], v[106:109]
	v_mfma_f32_16x16x32_f16 v[102:105], v[170:173], v[134:137], v[102:105]
	v_mfma_f32_16x16x32_f16 v[98:101], v[174:177], v[134:137], v[98:101]
	v_mfma_f32_16x16x32_f16 v[94:97], v[162:165], v[138:141], v[94:97]
	v_mfma_f32_16x16x32_f16 v[90:93], v[166:169], v[138:141], v[90:93]
	v_mfma_f32_16x16x32_f16 v[86:89], v[170:173], v[138:141], v[86:89]
	v_mfma_f32_16x16x32_f16 v[82:85], v[174:177], v[138:141], v[82:85]
	v_mfma_f32_16x16x32_f16 v[78:81], v[162:165], v[142:145], v[78:81]
	v_mfma_f32_16x16x32_f16 v[74:77], v[166:169], v[142:145], v[74:77]
	v_mfma_f32_16x16x32_f16 v[70:73], v[170:173], v[142:145], v[70:73]
	v_mfma_f32_16x16x32_f16 v[66:69], v[174:177], v[142:145], v[66:69]
	s_barrier
	ds_read_b128 v[146:149], v188 offset:8192
	ds_read_b128 v[150:153], v188 offset:10240
	ds_read_b128 v[154:157], v188 offset:12288
	ds_read_b128 v[158:161], v188 offset:14336
	s_add_u32 s22, s20, 0x40080
	s_add_i32 m0, s19, 0x1c000
	v_lshl_add_u64 v[196:197], v[228:229], 0, s[22:23]
	global_load_lds_dwordx4 v[196:197], off
	s_add_u32 s22, s20, 0x60080
	s_add_i32 m0, s19, 0x1e000
	v_lshl_add_u64 v[198:199], v[228:229], 0, s[22:23]
	global_load_lds_dwordx4 v[198:199], off
	s_waitcnt lgkmcnt(0)
	s_barrier
	v_mfma_f32_16x16x32_f16 v[62:65], v[162:165], v[146:149], v[62:65]
	v_mfma_f32_16x16x32_f16 v[58:61], v[166:169], v[146:149], v[58:61]
	v_mfma_f32_16x16x32_f16 v[54:57], v[170:173], v[146:149], v[54:57]
	v_mfma_f32_16x16x32_f16 v[50:53], v[174:177], v[146:149], v[50:53]
	v_mfma_f32_16x16x32_f16 v[46:49], v[162:165], v[150:153], v[46:49]
	v_mfma_f32_16x16x32_f16 v[42:45], v[166:169], v[150:153], v[42:45]
	v_mfma_f32_16x16x32_f16 v[38:41], v[170:173], v[150:153], v[38:41]
	v_mfma_f32_16x16x32_f16 v[34:37], v[174:177], v[150:153], v[34:37]
	v_mfma_f32_16x16x32_f16 v[30:33], v[162:165], v[154:157], v[30:33]
	v_mfma_f32_16x16x32_f16 v[26:29], v[166:169], v[154:157], v[26:29]
	v_mfma_f32_16x16x32_f16 v[22:25], v[170:173], v[154:157], v[22:25]
	v_mfma_f32_16x16x32_f16 v[18:21], v[174:177], v[154:157], v[18:21]
	v_mfma_f32_16x16x32_f16 v[14:17], v[162:165], v[158:161], v[14:17]
	v_mfma_f32_16x16x32_f16 v[10:13], v[166:169], v[158:161], v[10:13]
	v_mfma_f32_16x16x32_f16 v[6:9], v[170:173], v[158:161], v[6:9]
	v_mfma_f32_16x16x32_f16 v[2:5], v[174:177], v[158:161], v[2:5]
	s_barrier
	ds_read_b128 v[130:133], v189 offset:0
	ds_read_b128 v[134:137], v189 offset:2048
	ds_read_b128 v[138:141], v189 offset:4096
	ds_read_b128 v[142:145], v189 offset:6144
	ds_read_b128 v[162:165], v191 offset:32768
	ds_read_b128 v[166:169], v191 offset:34816
	ds_read_b128 v[170:173], v191 offset:36864
	ds_read_b128 v[174:177], v191 offset:38912
	s_add_u32 s22, s20, 0x80
	s_add_i32 m0, s19, 0x12000
	v_lshl_add_u64 v[196:197], v[220:221], 0, s[22:23]
	global_load_lds_dwordx4 v[196:197], off
	s_add_u32 s22, s20, 0x80
	s_add_i32 m0, s19, 0x16000
	v_lshl_add_u64 v[198:199], v[226:227], 0, s[22:23]
	global_load_lds_dwordx4 v[198:199], off
	s_waitcnt lgkmcnt(0)
	s_barrier
	v_mfma_f32_16x16x32_f16 v[126:129], v[162:165], v[130:133], v[126:129]
	v_mfma_f32_16x16x32_f16 v[122:125], v[166:169], v[130:133], v[122:125]
	v_mfma_f32_16x16x32_f16 v[118:121], v[170:173], v[130:133], v[118:121]
	v_mfma_f32_16x16x32_f16 v[114:117], v[174:177], v[130:133], v[114:117]
	v_mfma_f32_16x16x32_f16 v[110:113], v[162:165], v[134:137], v[110:113]
	v_mfma_f32_16x16x32_f16 v[106:109], v[166:169], v[134:137], v[106:109]
	v_mfma_f32_16x16x32_f16 v[102:105], v[170:173], v[134:137], v[102:105]
	v_mfma_f32_16x16x32_f16 v[98:101], v[174:177], v[134:137], v[98:101]
	v_mfma_f32_16x16x32_f16 v[94:97], v[162:165], v[138:141], v[94:97]
	v_mfma_f32_16x16x32_f16 v[90:93], v[166:169], v[138:141], v[90:93]
	v_mfma_f32_16x16x32_f16 v[86:89], v[170:173], v[138:141], v[86:89]
	v_mfma_f32_16x16x32_f16 v[82:85], v[174:177], v[138:141], v[82:85]
	v_mfma_f32_16x16x32_f16 v[78:81], v[162:165], v[142:145], v[78:81]
	v_mfma_f32_16x16x32_f16 v[74:77], v[166:169], v[142:145], v[74:77]
	v_mfma_f32_16x16x32_f16 v[70:73], v[170:173], v[142:145], v[70:73]
	v_mfma_f32_16x16x32_f16 v[66:69], v[174:177], v[142:145], v[66:69]
	s_barrier
	ds_read_b128 v[146:149], v189 offset:8192
	ds_read_b128 v[150:153], v189 offset:10240
	ds_read_b128 v[154:157], v189 offset:12288
	ds_read_b128 v[158:161], v189 offset:14336
	s_waitcnt vmcnt(2) lgkmcnt(0)
	s_barrier
	v_mfma_f32_16x16x32_f16 v[62:65], v[162:165], v[146:149], v[62:65]
	v_mfma_f32_16x16x32_f16 v[58:61], v[166:169], v[146:149], v[58:61]
	v_mfma_f32_16x16x32_f16 v[54:57], v[170:173], v[146:149], v[54:57]
	v_mfma_f32_16x16x32_f16 v[50:53], v[174:177], v[146:149], v[50:53]
	v_mfma_f32_16x16x32_f16 v[46:49], v[162:165], v[150:153], v[46:49]
	v_mfma_f32_16x16x32_f16 v[42:45], v[166:169], v[150:153], v[42:45]
	v_mfma_f32_16x16x32_f16 v[38:41], v[170:173], v[150:153], v[38:41]
	v_mfma_f32_16x16x32_f16 v[34:37], v[174:177], v[150:153], v[34:37]
	v_mfma_f32_16x16x32_f16 v[30:33], v[162:165], v[154:157], v[30:33]
	v_mfma_f32_16x16x32_f16 v[26:29], v[166:169], v[154:157], v[26:29]
	v_mfma_f32_16x16x32_f16 v[22:25], v[170:173], v[154:157], v[22:25]
	v_mfma_f32_16x16x32_f16 v[18:21], v[174:177], v[154:157], v[18:21]
	v_mfma_f32_16x16x32_f16 v[14:17], v[162:165], v[158:161], v[14:17]
	v_mfma_f32_16x16x32_f16 v[10:13], v[166:169], v[158:161], v[10:13]
	v_mfma_f32_16x16x32_f16 v[6:9], v[170:173], v[158:161], v[6:9]
	v_mfma_f32_16x16x32_f16 v[2:5], v[174:177], v[158:161], v[2:5]
	s_barrier
	s_add_u32 s20, s20, 0x80
	ds_read_b128 v[130:133], v192 offset:0
	ds_read_b128 v[134:137], v192 offset:2048
	ds_read_b128 v[138:141], v192 offset:4096
	ds_read_b128 v[142:145], v192 offset:6144
	ds_read_b128 v[162:165], v194 offset:32768
	ds_read_b128 v[166:169], v194 offset:34816
	ds_read_b128 v[170:173], v194 offset:36864
	ds_read_b128 v[174:177], v194 offset:38912
	s_waitcnt vmcnt(0) lgkmcnt(0)
	s_barrier
	v_mfma_f32_16x16x32_f16 v[126:129], v[162:165], v[130:133], v[126:129]
	v_mfma_f32_16x16x32_f16 v[122:125], v[166:169], v[130:133], v[122:125]
	v_mfma_f32_16x16x32_f16 v[118:121], v[170:173], v[130:133], v[118:121]
	v_mfma_f32_16x16x32_f16 v[114:117], v[174:177], v[130:133], v[114:117]
	v_mfma_f32_16x16x32_f16 v[110:113], v[162:165], v[134:137], v[110:113]
	v_mfma_f32_16x16x32_f16 v[106:109], v[166:169], v[134:137], v[106:109]
	v_mfma_f32_16x16x32_f16 v[102:105], v[170:173], v[134:137], v[102:105]
	v_mfma_f32_16x16x32_f16 v[98:101], v[174:177], v[134:137], v[98:101]
	v_mfma_f32_16x16x32_f16 v[94:97], v[162:165], v[138:141], v[94:97]
	v_mfma_f32_16x16x32_f16 v[90:93], v[166:169], v[138:141], v[90:93]
	v_mfma_f32_16x16x32_f16 v[86:89], v[170:173], v[138:141], v[86:89]
	v_mfma_f32_16x16x32_f16 v[82:85], v[174:177], v[138:141], v[82:85]
	v_mfma_f32_16x16x32_f16 v[78:81], v[162:165], v[142:145], v[78:81]
	v_mfma_f32_16x16x32_f16 v[74:77], v[166:169], v[142:145], v[74:77]
	v_mfma_f32_16x16x32_f16 v[70:73], v[170:173], v[142:145], v[70:73]
	v_mfma_f32_16x16x32_f16 v[66:69], v[174:177], v[142:145], v[66:69]
	s_barrier
	ds_read_b128 v[146:149], v192 offset:8192
	ds_read_b128 v[150:153], v192 offset:10240
	ds_read_b128 v[154:157], v192 offset:12288
	ds_read_b128 v[158:161], v192 offset:14336
	s_waitcnt lgkmcnt(0)
	s_barrier
	v_mfma_f32_16x16x32_f16 v[62:65], v[162:165], v[146:149], v[62:65]
	v_mfma_f32_16x16x32_f16 v[58:61], v[166:169], v[146:149], v[58:61]
	v_mfma_f32_16x16x32_f16 v[54:57], v[170:173], v[146:149], v[54:57]
	v_mfma_f32_16x16x32_f16 v[50:53], v[174:177], v[146:149], v[50:53]
	v_mfma_f32_16x16x32_f16 v[46:49], v[162:165], v[150:153], v[46:49]
	v_mfma_f32_16x16x32_f16 v[42:45], v[166:169], v[150:153], v[42:45]
	v_mfma_f32_16x16x32_f16 v[38:41], v[170:173], v[150:153], v[38:41]
	v_mfma_f32_16x16x32_f16 v[34:37], v[174:177], v[150:153], v[34:37]
	v_mfma_f32_16x16x32_f16 v[30:33], v[162:165], v[154:157], v[30:33]
	v_mfma_f32_16x16x32_f16 v[26:29], v[166:169], v[154:157], v[26:29]
	v_mfma_f32_16x16x32_f16 v[22:25], v[170:173], v[154:157], v[22:25]
	v_mfma_f32_16x16x32_f16 v[18:21], v[174:177], v[154:157], v[18:21]
	v_mfma_f32_16x16x32_f16 v[14:17], v[162:165], v[158:161], v[14:17]
	v_mfma_f32_16x16x32_f16 v[10:13], v[166:169], v[158:161], v[10:13]
	v_mfma_f32_16x16x32_f16 v[6:9], v[170:173], v[158:161], v[6:9]
	v_mfma_f32_16x16x32_f16 v[2:5], v[174:177], v[158:161], v[2:5]
	s_barrier
	ds_read_b128 v[130:133], v193 offset:0
	ds_read_b128 v[134:137], v193 offset:2048
	ds_read_b128 v[138:141], v193 offset:4096
	ds_read_b128 v[142:145], v193 offset:6144
	ds_read_b128 v[162:165], v195 offset:32768
	ds_read_b128 v[166:169], v195 offset:34816
	ds_read_b128 v[170:173], v195 offset:36864
	ds_read_b128 v[174:177], v195 offset:38912
	s_waitcnt lgkmcnt(0)
	s_barrier
	v_mfma_f32_16x16x32_f16 v[126:129], v[162:165], v[130:133], v[126:129]
	v_mfma_f32_16x16x32_f16 v[122:125], v[166:169], v[130:133], v[122:125]
	v_mfma_f32_16x16x32_f16 v[118:121], v[170:173], v[130:133], v[118:121]
	v_mfma_f32_16x16x32_f16 v[114:117], v[174:177], v[130:133], v[114:117]
	v_mfma_f32_16x16x32_f16 v[110:113], v[162:165], v[134:137], v[110:113]
	v_mfma_f32_16x16x32_f16 v[106:109], v[166:169], v[134:137], v[106:109]
	v_mfma_f32_16x16x32_f16 v[102:105], v[170:173], v[134:137], v[102:105]
	v_mfma_f32_16x16x32_f16 v[98:101], v[174:177], v[134:137], v[98:101]
	v_mfma_f32_16x16x32_f16 v[94:97], v[162:165], v[138:141], v[94:97]
	v_mfma_f32_16x16x32_f16 v[90:93], v[166:169], v[138:141], v[90:93]
	v_mfma_f32_16x16x32_f16 v[86:89], v[170:173], v[138:141], v[86:89]
	v_mfma_f32_16x16x32_f16 v[82:85], v[174:177], v[138:141], v[82:85]
	v_mfma_f32_16x16x32_f16 v[78:81], v[162:165], v[142:145], v[78:81]
	v_mfma_f32_16x16x32_f16 v[74:77], v[166:169], v[142:145], v[74:77]
	v_mfma_f32_16x16x32_f16 v[70:73], v[170:173], v[142:145], v[70:73]
	v_mfma_f32_16x16x32_f16 v[66:69], v[174:177], v[142:145], v[66:69]
	s_barrier
	ds_read_b128 v[146:149], v193 offset:8192
	ds_read_b128 v[150:153], v193 offset:10240
	ds_read_b128 v[154:157], v193 offset:12288
	ds_read_b128 v[158:161], v193 offset:14336
	s_waitcnt lgkmcnt(0)
	s_barrier
	v_mfma_f32_16x16x32_f16 v[62:65], v[162:165], v[146:149], v[62:65]
	v_mfma_f32_16x16x32_f16 v[58:61], v[166:169], v[146:149], v[58:61]
	v_mfma_f32_16x16x32_f16 v[54:57], v[170:173], v[146:149], v[54:57]
	v_mfma_f32_16x16x32_f16 v[50:53], v[174:177], v[146:149], v[50:53]
	v_mfma_f32_16x16x32_f16 v[46:49], v[162:165], v[150:153], v[46:49]
	v_mfma_f32_16x16x32_f16 v[42:45], v[166:169], v[150:153], v[42:45]
	v_mfma_f32_16x16x32_f16 v[38:41], v[170:173], v[150:153], v[38:41]
	v_mfma_f32_16x16x32_f16 v[34:37], v[174:177], v[150:153], v[34:37]
	v_mfma_f32_16x16x32_f16 v[30:33], v[162:165], v[154:157], v[30:33]
	v_mfma_f32_16x16x32_f16 v[26:29], v[166:169], v[154:157], v[26:29]
	v_mfma_f32_16x16x32_f16 v[22:25], v[170:173], v[154:157], v[22:25]
	v_mfma_f32_16x16x32_f16 v[18:21], v[174:177], v[154:157], v[18:21]
	v_mfma_f32_16x16x32_f16 v[14:17], v[162:165], v[158:161], v[14:17]
	v_mfma_f32_16x16x32_f16 v[10:13], v[166:169], v[158:161], v[10:13]
	v_mfma_f32_16x16x32_f16 v[6:9], v[170:173], v[158:161], v[6:9]
	v_mfma_f32_16x16x32_f16 v[2:5], v[174:177], v[158:161], v[2:5]
	s_barrier
	s_cmp_eq_u32 s29, 1
	s_cbranch_scc1 .Lp4_skew1
	s_barrier
.Lp4_skew1:
	s_nop 7
	s_nop 1
	s_mov_b32 s94, s18
	s_mov_b32 s34, s28
	v_bfe_u32 v201, v222, 6, 2
	v_bfe_u32 v202, v222, 4, 2
	v_lshlrev_b32_e32 v203, 2, v202
	v_lshl_or_b32 v203, v201, 5, v203
	s_lshl_b32 s4, s94, 7
	v_or_b32_e32 v204, s4, v203
	v_lshlrev_b32_e32 v205, 2, v204
	global_load_dwordx4 v[130:133], v205, s[10:11]
	global_load_dwordx4 v[134:137], v205, s[12:13]
	global_load_dwordx4 v[138:141], v205, s[14:15]
	global_load_dwordx4 v[142:145], v205, s[10:11] offset:64
	global_load_dwordx4 v[146:149], v205, s[12:13] offset:64
	global_load_dwordx4 v[150:153], v205, s[14:15] offset:64
	s_add_i32 s2, s49, s95
	s_cmp_lt_i32 s2, s58
	s_cselect_b32 s35, 1, 0
	s_cselect_b32 s49, s2, s49
	s_mul_hi_i32 s2, s49, 0x2e8ba2e9
	s_lshr_b32 s3, s2, 31
	s_ashr_i32 s2, s2, 6
	s_add_i32 s2, s2, s3
	s_lshl_b32 s3, s2, 4
	s_sub_i32 s4, s7, s3
	s_min_i32 s4, s4, 16
	s_abs_i32 s5, s4
	v_cvt_f32_u32_e32 v199, s5
	s_sub_i32 s20, 0, s5
	s_mulk_i32 s2, 0xfea0
	s_add_i32 s2, s2, s49
	v_rcp_iflag_f32_e32 v199, v199
	s_abs_i32 s19, s2
	s_xor_b32 s18, s2, s4
	s_ashr_i32 s18, s18, 31
	v_mul_f32_e32 v199, 0x4f7ffffe, v199
	v_cvt_u32_f32_e32 v199, v199
	s_nop 1
	v_readfirstlane_b32 s21, v199
	s_mul_i32 s20, s20, s21
	s_mul_hi_u32 s20, s21, s20
	s_add_i32 s21, s21, s20
	s_mul_hi_u32 s20, s19, s21
	s_mul_i32 s21, s20, s5
	s_sub_i32 s19, s19, s21
	s_add_i32 s21, s20, 1
	s_sub_i32 s22, s19, s5
	s_cmp_ge_u32 s19, s5
	s_cselect_b32 s20, s21, s20
	s_cselect_b32 s19, s22, s19
	s_add_i32 s21, s20, 1
	s_cmp_ge_u32 s19, s5
	s_cselect_b32 s5, s21, s20
	s_xor_b32 s5, s5, s18
	s_sub_i32 s18, s5, s18
	s_mul_i32 s4, s18, s4
	s_sub_i32 s2, s2, s4
	s_add_i32 s2, s2, s3
	s_mul_i32 s28, s2, 0xfe
	s_add_i32 s28, s28, -1
	v_lshrrev_b32_e32 v202, 3, v222
	v_lshrrev_b32_e32 v203, 4, v222
	v_xor_b32_e32 v203, v203, v222
	v_and_b32_e32 v203, 7, v203
	v_lshlrev_b32_e32 v210, 4, v203
	v_mov_b32_e32 v200, s46
	v_mov_b32_e32 v201, s47
	v_add_u32_e32 v204, s28, v202
	v_mov_b32_e32 v205, 0
	v_cmp_gt_u32_e32 vcc, s6, v204
	v_lshlrev_b64 v[196:197], 11, v[204:205]
	v_lshl_add_u64 v[196:197], s[64:65], 0, v[196:197]
	v_cndmask_b32_e32 v196, v200, v196, vcc
	v_cndmask_b32_e32 v197, v201, v197, vcc
	v_lshl_add_u64 v[218:219], v[196:197], 0, v[210:211]
	v_add_u32_e32 v204, 64, v204
	v_cmp_gt_u32_e32 vcc, s6, v204
	v_lshlrev_b64 v[196:197], 11, v[204:205]
	v_lshl_add_u64 v[196:197], s[64:65], 0, v[196:197]
	v_cndmask_b32_e32 v196, v200, v196, vcc
	v_cndmask_b32_e32 v197, v201, v197, vcc
	v_lshl_add_u64 v[220:221], v[196:197], 0, v[210:211]
	v_add_u32_e32 v204, 64, v204
	v_cmp_gt_u32_e32 vcc, s6, v204
	v_lshlrev_b64 v[196:197], 11, v[204:205]
	v_lshl_add_u64 v[196:197], s[64:65], 0, v[196:197]
	v_cndmask_b32_e32 v196, v200, v196, vcc
	v_cndmask_b32_e32 v197, v201, v197, vcc
	v_lshl_add_u64 v[224:225], v[196:197], 0, v[210:211]
	v_add_u32_e32 v204, 64, v204
	v_cmp_gt_u32_e32 vcc, s6, v204
	v_lshlrev_b64 v[196:197], 11, v[204:205]
	v_lshl_add_u64 v[196:197], s[64:65], 0, v[196:197]
	v_cndmask_b32_e32 v196, v200, v196, vcc
	v_cndmask_b32_e32 v197, v201, v197, vcc
	v_lshl_add_u64 v[226:227], v[196:197], 0, v[210:211]
	s_lshl_b32 s2, s18, 19
	s_add_u32 s2, s55, s2
	s_addc_u32 s3, s48, 0
	v_lshlrev_b32_e32 v196, 11, v202
	v_add_u32_e32 v196, v196, v210
	v_mov_b32_e32 v197, 0
	v_lshl_add_u64 v[228:229], v[196:197], 0, s[2:3]
	v_readfirstlane_b32 s19, v222
	s_nop 3
	s_lshr_b32 s29, s19, 8
	s_lshr_b32 s19, s19, 6
	s_lshl_b32 s19, s19, 10
	s_mov_b32 s20, 0
	s_mov_b32 s21, 0
	s_mov_b32 s23, 0
	s_mov_b32 m0, s19
	v_lshl_add_u64 v[196:197], v[218:219], 0, s[20:21]
	global_load_lds_dwordx4 v[196:197], off
	s_add_i32 m0, s19, 0x2000
	v_lshl_add_u64 v[198:199], v[220:221], 0, s[20:21]
	global_load_lds_dwordx4 v[198:199], off
	s_add_i32 m0, s19, 0x4000
	v_lshl_add_u64 v[196:197], v[224:225], 0, s[20:21]
	global_load_lds_dwordx4 v[196:197], off
	s_add_i32 m0, s19, 0x6000
	v_lshl_add_u64 v[198:199], v[226:227], 0, s[20:21]
	global_load_lds_dwordx4 v[198:199], off
	s_add_i32 m0, s19, 0x8000
	v_lshl_add_u64 v[196:197], v[228:229], 0, s[20:21]
	global_load_lds_dwordx4 v[196:197], off
	s_add_u32 s22, s20, 0x20000
	s_add_i32 m0, s19, 0xa000
	v_lshl_add_u64 v[198:199], v[228:229], 0, s[22:23]
	global_load_lds_dwordx4 v[198:199], off
	s_add_u32 s22, s20, 0x40000
	s_add_i32 m0, s19, 0xc000
	v_lshl_add_u64 v[196:197], v[228:229], 0, s[22:23]
	global_load_lds_dwordx4 v[196:197], off
	s_add_u32 s22, s20, 0x60000
	s_add_i32 m0, s19, 0xe000
	v_lshl_add_u64 v[198:199], v[228:229], 0, s[22:23]
	global_load_lds_dwordx4 v[198:199], off
	v_and_b32_e32 v200, 15, v222
	v_lshrrev_b32_e32 v201, 8, v222
	v_lshl_or_b32 v200, v201, 7, v200
	v_bfe_u32 v201, v222, 6, 2
	v_bfe_u32 v202, v222, 4, 2
	v_lshlrev_b32_e32 v203, 2, v202
	v_lshl_or_b32 v203, v201, 5, v203
	s_lshl_b32 s4, s94, 7
	v_or_b32_e32 v204, s4, v203
	v_lshlrev_b32_e32 v205, 2, v204
	v_lshlrev_b32_e32 v207, 1, v204
	v_mul_u32_u24_e32 v206, 0x110, v200
	v_lshl_add_u32 v206, v203, 1, v206
	v_add_u32_e32 v206, 0x10000, v206
	v_cvt_pk_f16_f32 v170, v126, v127
	v_cvt_pk_f16_f32 v171, v128, v129
	v_cvt_pk_f16_f32 v172, v118, v119
	v_cvt_pk_f16_f32 v173, v120, v121
	ds_write2_b64 v206, v[170:171], v[172:173] offset1:4
	v_cvt_pk_f16_f32 v174, v110, v111
	v_cvt_pk_f16_f32 v175, v112, v113
	v_cvt_pk_f16_f32 v176, v102, v103
	v_cvt_pk_f16_f32 v177, v104, v105
	v_add_u32_e32 v178, 0x1100, v206
	ds_write2_b64 v178, v[174:175], v[176:177] offset1:4
	v_cvt_pk_f16_f32 v170, v94, v95
	v_cvt_pk_f16_f32 v171, v96, v97
	v_cvt_pk_f16_f32 v172, v86, v87
	v_cvt_pk_f16_f32 v173, v88, v89
	v_add_u32_e32 v178, 0x2200, v206
	ds_write2_b64 v178, v[170:171], v[172:173] offset1:4
	v_cvt_pk_f16_f32 v174, v78, v79
	v_cvt_pk_f16_f32 v175, v80, v81
	v_cvt_pk_f16_f32 v176, v70, v71
	v_cvt_pk_f16_f32 v177, v72, v73
	v_add_u32_e32 v178, 0x3300, v206
	ds_write2_b64 v178, v[174:175], v[176:177] offset1:4
	v_cvt_pk_f16_f32 v170, v62, v63
	v_cvt_pk_f16_f32 v171, v64, v65
	v_cvt_pk_f16_f32 v172, v54, v55
	v_cvt_pk_f16_f32 v173, v56, v57
	v_add_u32_e32 v178, 0x4400, v206
	ds_write2_b64 v178, v[170:171], v[172:173] offset1:4
	v_cvt_pk_f16_f32 v174, v46, v47
	v_cvt_pk_f16_f32 v175, v48, v49
	v_cvt_pk_f16_f32 v176, v38, v39
	v_cvt_pk_f16_f32 v177, v40, v41
	v_add_u32_e32 v178, 0x5500, v206
	ds_write2_b64 v178, v[174:175], v[176:177] offset1:4
	v_cvt_pk_f16_f32 v170, v30, v31
	v_cvt_pk_f16_f32 v171, v32, v33
	v_cvt_pk_f16_f32 v172, v22, v23
	v_cvt_pk_f16_f32 v173, v24, v25
	v_add_u32_e32 v178, 0x6600, v206
	ds_write2_b64 v178, v[170:171], v[172:173] offset1:4
	v_cvt_pk_f16_f32 v174, v14, v15
	v_cvt_pk_f16_f32 v175, v16, v17
	v_cvt_pk_f16_f32 v176, v6, v7
	v_cvt_pk_f16_f32 v177, v8, v9
	v_add_u32_e32 v178, 0x7700, v206
	ds_write2_b64 v178, v[174:175], v[176:177] offset1:4
	v_add_u32_e32 v201, 0xfffffef0, v206
	s_waitcnt lgkmcnt(0)
	s_barrier
	ds_read2_b64 v[154:157], v201 offset1:4
	ds_read2_b64 v[158:161], v201 offset0:68 offset1:72
	s_waitcnt vmcnt(8)
	v_add_u32_e32 v179, 0x1100, v201
	ds_read2_b64 v[162:165], v179 offset1:4
	ds_read2_b64 v[166:169], v179 offset0:68 offset1:72
	v_add_u32_e32 v180, 0, v200
	v_add_u32_e32 v181, s34, v180
	v_add_u32_e32 v182, -1, v180
	v_cmp_gt_u32_e32 vcc, 0xfe, v182
	v_cmp_gt_i32_e64 s[2:3], s6, v181
	v_cmp_gt_i32_e64 s[4:5], s68, v181
	v_mad_u32_u24 v183, v181, s52, v207
	s_and_b64 s[2:3], vcc, s[2:3]
	v_cndmask_b32_e64 v184, v216, v217, s[4:5]
	v_and_b32_e32 v185, v184, v181
	v_cmp_eq_u32_e32 vcc, 0, v185
	s_nop 1
	v_cndmask_b32_e64 v186, 1.0, 0, vcc
	v_cmp_eq_u32_e32 vcc, v185, v184
	s_nop 1
	v_cndmask_b32_e64 v188, 1.0, 0, vcc
	s_and_saveexec_b64 s[4:5], s[2:3]
	s_waitcnt lgkmcnt(2)
	v_pk_mul_f32 v[126:127], v[126:127], v[134:135]
	v_pk_mul_f32 v[128:129], v[128:129], v[136:137]
	v_pk_mul_f32 v[190:191], v[186:187], v[130:131] op_sel_hi:[0,1]
	v_pk_mul_f32 v[192:193], v[186:187], v[132:133] op_sel_hi:[0,1]
	v_cvt_f32_f16_e32 v194, v154
	v_cvt_f32_f16_sdwa v195, v154 dst_sel:DWORD dst_unused:UNUSED_PAD src0_sel:WORD_1
	v_cvt_f32_f16_e32 v196, v155
	v_cvt_f32_f16_sdwa v197, v155 dst_sel:DWORD dst_unused:UNUSED_PAD src0_sel:WORD_1
	v_pk_fma_f32 v[126:127], v[190:191], v[194:195], v[126:127]
	v_pk_fma_f32 v[128:129], v[192:193], v[196:197], v[128:129]
	v_pk_mul_f32 v[190:191], v[188:189], v[138:139] op_sel_hi:[0,1]
	v_pk_mul_f32 v[192:193], v[188:189], v[140:141] op_sel_hi:[0,1]
	v_cvt_f32_f16_e32 v194, v158
	v_cvt_f32_f16_sdwa v195, v158 dst_sel:DWORD dst_unused:UNUSED_PAD src0_sel:WORD_1
	v_cvt_f32_f16_e32 v196, v159
	v_cvt_f32_f16_sdwa v197, v159 dst_sel:DWORD dst_unused:UNUSED_PAD src0_sel:WORD_1
	v_pk_fma_f32 v[126:127], v[190:191], v[194:195], v[126:127]
	v_pk_fma_f32 v[128:129], v[192:193], v[196:197], v[128:129]
	v_mul_f32_e32 v190, 0xbfb8aa3b, v126
	v_mul_f32_e32 v191, 0xbfb8aa3b, v127
	v_mul_f32_e32 v192, 0xbfb8aa3b, v128
	v_mul_f32_e32 v193, 0xbfb8aa3b, v129
	v_exp_f32_e32 v190, v190
	v_exp_f32_e32 v191, v191
	v_exp_f32_e32 v192, v192
	v_exp_f32_e32 v193, v193
	v_add_f32_e32 v190, 1.0, v190
	v_add_f32_e32 v191, 1.0, v191
	v_add_f32_e32 v192, 1.0, v192
	v_add_f32_e32 v193, 1.0, v193
	v_rcp_f32_e32 v190, v190
	v_rcp_f32_e32 v191, v191
	v_rcp_f32_e32 v192, v192
	v_rcp_f32_e32 v193, v193
	s_nop 0
	v_pk_mul_f32 v[126:127], v[126:127], v[190:191]
	v_pk_mul_f32 v[128:129], v[128:129], v[192:193]
	v_pk_mul_f32 v[126:127], v[122:123], v[126:127]
	v_pk_mul_f32 v[128:129], v[124:125], v[128:129]
	v_cvt_pk_f16_f32 v126, v126, v127
	v_cvt_pk_f16_f32 v127, v128, v129
	global_store_dwordx2 v183, v[126:127], s[96:97]
	v_pk_mul_f32 v[118:119], v[118:119], v[146:147]
	v_pk_mul_f32 v[120:121], v[120:121], v[148:149]
	v_pk_mul_f32 v[190:191], v[186:187], v[142:143] op_sel_hi:[0,1]
	v_pk_mul_f32 v[192:193], v[186:187], v[144:145] op_sel_hi:[0,1]
	v_cvt_f32_f16_e32 v194, v156
	v_cvt_f32_f16_sdwa v195, v156 dst_sel:DWORD dst_unused:UNUSED_PAD src0_sel:WORD_1
	v_cvt_f32_f16_e32 v196, v157
	v_cvt_f32_f16_sdwa v197, v157 dst_sel:DWORD dst_unused:UNUSED_PAD src0_sel:WORD_1
	v_pk_fma_f32 v[118:119], v[190:191], v[194:195], v[118:119]
	v_pk_fma_f32 v[120:121], v[192:193], v[196:197], v[120:121]
	v_pk_mul_f32 v[190:191], v[188:189], v[150:151] op_sel_hi:[0,1]
	v_pk_mul_f32 v[192:193], v[188:189], v[152:153] op_sel_hi:[0,1]
	v_cvt_f32_f16_e32 v194, v160
	v_cvt_f32_f16_sdwa v195, v160 dst_sel:DWORD dst_unused:UNUSED_PAD src0_sel:WORD_1
	v_cvt_f32_f16_e32 v196, v161
	v_cvt_f32_f16_sdwa v197, v161 dst_sel:DWORD dst_unused:UNUSED_PAD src0_sel:WORD_1
	v_pk_fma_f32 v[118:119], v[190:191], v[194:195], v[118:119]
	v_pk_fma_f32 v[120:121], v[192:193], v[196:197], v[120:121]
	v_mul_f32_e32 v190, 0xbfb8aa3b, v118
	v_mul_f32_e32 v191, 0xbfb8aa3b, v119
	v_mul_f32_e32 v192, 0xbfb8aa3b, v120
	v_mul_f32_e32 v193, 0xbfb8aa3b, v121
	v_exp_f32_e32 v190, v190
	v_exp_f32_e32 v191, v191
	v_exp_f32_e32 v192, v192
	v_exp_f32_e32 v193, v193
	v_add_f32_e32 v190, 1.0, v190
	v_add_f32_e32 v191, 1.0, v191
	v_add_f32_e32 v192, 1.0, v192
	v_add_f32_e32 v193, 1.0, v193
	v_rcp_f32_e32 v190, v190
	v_rcp_f32_e32 v191, v191
	v_rcp_f32_e32 v192, v192
	v_rcp_f32_e32 v193, v193
	s_nop 0
	v_pk_mul_f32 v[118:119], v[118:119], v[190:191]
	v_pk_mul_f32 v[120:121], v[120:121], v[192:193]
	v_pk_mul_f32 v[118:119], v[114:115], v[118:119]
	v_pk_mul_f32 v[120:121], v[116:117], v[120:121]
	v_cvt_pk_f16_f32 v118, v118, v119
	v_cvt_pk_f16_f32 v119, v120, v121
	global_store_dwordx2 v183, v[118:119], s[96:97] offset:32
	s_mov_b64 exec, s[4:5]
	v_add_u32_e32 v179, 0x2200, v201
	ds_read2_b64 v[154:157], v179 offset1:4
	ds_read2_b64 v[158:161], v179 offset0:68 offset1:72
	v_add_u32_e32 v180, 16, v200
	v_add_u32_e32 v181, s34, v180
	v_add_u32_e32 v182, -1, v180
	v_cmp_gt_u32_e32 vcc, 0xfe, v182
	v_cmp_gt_i32_e64 s[2:3], s6, v181
	v_cmp_gt_i32_e64 s[4:5], s68, v181
	v_mad_u32_u24 v183, v181, s52, v207
	s_and_b64 s[2:3], vcc, s[2:3]
	v_cndmask_b32_e64 v184, v216, v217, s[4:5]
	v_and_b32_e32 v185, v184, v181
	v_cmp_eq_u32_e32 vcc, 0, v185
	s_nop 1
	v_cndmask_b32_e64 v186, 1.0, 0, vcc
	v_cmp_eq_u32_e32 vcc, v185, v184
	s_nop 1
	v_cndmask_b32_e64 v188, 1.0, 0, vcc
	s_and_saveexec_b64 s[4:5], s[2:3]
	s_waitcnt lgkmcnt(2)
	v_pk_mul_f32 v[110:111], v[110:111], v[134:135]
	v_pk_mul_f32 v[112:113], v[112:113], v[136:137]
	v_pk_mul_f32 v[190:191], v[186:187], v[130:131] op_sel_hi:[0,1]
	v_pk_mul_f32 v[192:193], v[186:187], v[132:133] op_sel_hi:[0,1]
	v_cvt_f32_f16_e32 v194, v162
	v_cvt_f32_f16_sdwa v195, v162 dst_sel:DWORD dst_unused:UNUSED_PAD src0_sel:WORD_1
	v_cvt_f32_f16_e32 v196, v163
	v_cvt_f32_f16_sdwa v197, v163 dst_sel:DWORD dst_unused:UNUSED_PAD src0_sel:WORD_1
	v_pk_fma_f32 v[110:111], v[190:191], v[194:195], v[110:111]
	v_pk_fma_f32 v[112:113], v[192:193], v[196:197], v[112:113]
	v_pk_mul_f32 v[190:191], v[188:189], v[138:139] op_sel_hi:[0,1]
	v_pk_mul_f32 v[192:193], v[188:189], v[140:141] op_sel_hi:[0,1]
	v_cvt_f32_f16_e32 v194, v166
	v_cvt_f32_f16_sdwa v195, v166 dst_sel:DWORD dst_unused:UNUSED_PAD src0_sel:WORD_1
	v_cvt_f32_f16_e32 v196, v167
	v_cvt_f32_f16_sdwa v197, v167 dst_sel:DWORD dst_unused:UNUSED_PAD src0_sel:WORD_1
	v_pk_fma_f32 v[110:111], v[190:191], v[194:195], v[110:111]
	v_pk_fma_f32 v[112:113], v[192:193], v[196:197], v[112:113]
	v_mul_f32_e32 v190, 0xbfb8aa3b, v110
	v_mul_f32_e32 v191, 0xbfb8aa3b, v111
	v_mul_f32_e32 v192, 0xbfb8aa3b, v112
	v_mul_f32_e32 v193, 0xbfb8aa3b, v113
	v_exp_f32_e32 v190, v190
	v_exp_f32_e32 v191, v191
	v_exp_f32_e32 v192, v192
	v_exp_f32_e32 v193, v193
	v_add_f32_e32 v190, 1.0, v190
	v_add_f32_e32 v191, 1.0, v191
	v_add_f32_e32 v192, 1.0, v192
	v_add_f32_e32 v193, 1.0, v193
	v_rcp_f32_e32 v190, v190
	v_rcp_f32_e32 v191, v191
	v_rcp_f32_e32 v192, v192
	v_rcp_f32_e32 v193, v193
	s_nop 0
	v_pk_mul_f32 v[110:111], v[110:111], v[190:191]
	v_pk_mul_f32 v[112:113], v[112:113], v[192:193]
	v_pk_mul_f32 v[110:111], v[106:107], v[110:111]
	v_pk_mul_f32 v[112:113], v[108:109], v[112:113]
	v_cvt_pk_f16_f32 v110, v110, v111
	v_cvt_pk_f16_f32 v111, v112, v113
	global_store_dwordx2 v183, v[110:111], s[96:97]
	v_pk_mul_f32 v[102:103], v[102:103], v[146:147]
	v_pk_mul_f32 v[104:105], v[104:105], v[148:149]
	v_pk_mul_f32 v[190:191], v[186:187], v[142:143] op_sel_hi:[0,1]
	v_pk_mul_f32 v[192:193], v[186:187], v[144:145] op_sel_hi:[0,1]
	v_cvt_f32_f16_e32 v194, v164
	v_cvt_f32_f16_sdwa v195, v164 dst_sel:DWORD dst_unused:UNUSED_PAD src0_sel:WORD_1
	v_cvt_f32_f16_e32 v196, v165
	v_cvt_f32_f16_sdwa v197, v165 dst_sel:DWORD dst_unused:UNUSED_PAD src0_sel:WORD_1
	v_pk_fma_f32 v[102:103], v[190:191], v[194:195], v[102:103]
	v_pk_fma_f32 v[104:105], v[192:193], v[196:197], v[104:105]
	v_pk_mul_f32 v[190:191], v[188:189], v[150:151] op_sel_hi:[0,1]
	v_pk_mul_f32 v[192:193], v[188:189], v[152:153] op_sel_hi:[0,1]
	v_cvt_f32_f16_e32 v194, v168
	v_cvt_f32_f16_sdwa v195, v168 dst_sel:DWORD dst_unused:UNUSED_PAD src0_sel:WORD_1
	v_cvt_f32_f16_e32 v196, v169
	v_cvt_f32_f16_sdwa v197, v169 dst_sel:DWORD dst_unused:UNUSED_PAD src0_sel:WORD_1
	v_pk_fma_f32 v[102:103], v[190:191], v[194:195], v[102:103]
	v_pk_fma_f32 v[104:105], v[192:193], v[196:197], v[104:105]
	v_mul_f32_e32 v190, 0xbfb8aa3b, v102
	v_mul_f32_e32 v191, 0xbfb8aa3b, v103
	v_mul_f32_e32 v192, 0xbfb8aa3b, v104
	v_mul_f32_e32 v193, 0xbfb8aa3b, v105
	v_exp_f32_e32 v190, v190
	v_exp_f32_e32 v191, v191
	v_exp_f32_e32 v192, v192
	v_exp_f32_e32 v193, v193
	v_add_f32_e32 v190, 1.0, v190
	v_add_f32_e32 v191, 1.0, v191
	v_add_f32_e32 v192, 1.0, v192
	v_add_f32_e32 v193, 1.0, v193
	v_rcp_f32_e32 v190, v190
	v_rcp_f32_e32 v191, v191
	v_rcp_f32_e32 v192, v192
	v_rcp_f32_e32 v193, v193
	s_nop 0
	v_pk_mul_f32 v[102:103], v[102:103], v[190:191]
	v_pk_mul_f32 v[104:105], v[104:105], v[192:193]
	v_pk_mul_f32 v[102:103], v[98:99], v[102:103]
	v_pk_mul_f32 v[104:105], v[100:101], v[104:105]
	v_cvt_pk_f16_f32 v102, v102, v103
	v_cvt_pk_f16_f32 v103, v104, v105
	global_store_dwordx2 v183, v[102:103], s[96:97] offset:32
	s_mov_b64 exec, s[4:5]
	v_add_u32_e32 v179, 0x3300, v201
	ds_read2_b64 v[162:165], v179 offset1:4
	ds_read2_b64 v[166:169], v179 offset0:68 offset1:72
	v_add_u32_e32 v180, 32, v200
	v_add_u32_e32 v181, s34, v180
	v_add_u32_e32 v182, -1, v180
	v_cmp_gt_u32_e32 vcc, 0xfe, v182
	v_cmp_gt_i32_e64 s[2:3], s6, v181
	v_cmp_gt_i32_e64 s[4:5], s68, v181
	v_mad_u32_u24 v183, v181, s52, v207
	s_and_b64 s[2:3], vcc, s[2:3]
	v_cndmask_b32_e64 v184, v216, v217, s[4:5]
	v_and_b32_e32 v185, v184, v181
	v_cmp_eq_u32_e32 vcc, 0, v185
	s_nop 1
	v_cndmask_b32_e64 v186, 1.0, 0, vcc
	v_cmp_eq_u32_e32 vcc, v185, v184
	s_nop 1
	v_cndmask_b32_e64 v188, 1.0, 0, vcc
	s_and_saveexec_b64 s[4:5], s[2:3]
	s_waitcnt lgkmcnt(2)
	v_pk_mul_f32 v[94:95], v[94:95], v[134:135]
	v_pk_mul_f32 v[96:97], v[96:97], v[136:137]
	v_pk_mul_f32 v[190:191], v[186:187], v[130:131] op_sel_hi:[0,1]
	v_pk_mul_f32 v[192:193], v[186:187], v[132:133] op_sel_hi:[0,1]
	v_cvt_f32_f16_e32 v194, v154
	v_cvt_f32_f16_sdwa v195, v154 dst_sel:DWORD dst_unused:UNUSED_PAD src0_sel:WORD_1
	v_cvt_f32_f16_e32 v196, v155
	v_cvt_f32_f16_sdwa v197, v155 dst_sel:DWORD dst_unused:UNUSED_PAD src0_sel:WORD_1
	v_pk_fma_f32 v[94:95], v[190:191], v[194:195], v[94:95]
	v_pk_fma_f32 v[96:97], v[192:193], v[196:197], v[96:97]
	v_pk_mul_f32 v[190:191], v[188:189], v[138:139] op_sel_hi:[0,1]
	v_pk_mul_f32 v[192:193], v[188:189], v[140:141] op_sel_hi:[0,1]
	v_cvt_f32_f16_e32 v194, v158
	v_cvt_f32_f16_sdwa v195, v158 dst_sel:DWORD dst_unused:UNUSED_PAD src0_sel:WORD_1
	v_cvt_f32_f16_e32 v196, v159
	v_cvt_f32_f16_sdwa v197, v159 dst_sel:DWORD dst_unused:UNUSED_PAD src0_sel:WORD_1
	v_pk_fma_f32 v[94:95], v[190:191], v[194:195], v[94:95]
	v_pk_fma_f32 v[96:97], v[192:193], v[196:197], v[96:97]
	v_mul_f32_e32 v190, 0xbfb8aa3b, v94
	v_mul_f32_e32 v191, 0xbfb8aa3b, v95
	v_mul_f32_e32 v192, 0xbfb8aa3b, v96
	v_mul_f32_e32 v193, 0xbfb8aa3b, v97
	v_exp_f32_e32 v190, v190
	v_exp_f32_e32 v191, v191
	v_exp_f32_e32 v192, v192
	v_exp_f32_e32 v193, v193
	v_add_f32_e32 v190, 1.0, v190
	v_add_f32_e32 v191, 1.0, v191
	v_add_f32_e32 v192, 1.0, v192
	v_add_f32_e32 v193, 1.0, v193
	v_rcp_f32_e32 v190, v190
	v_rcp_f32_e32 v191, v191
	v_rcp_f32_e32 v192, v192
	v_rcp_f32_e32 v193, v193
	s_nop 0
	v_pk_mul_f32 v[94:95], v[94:95], v[190:191]
	v_pk_mul_f32 v[96:97], v[96:97], v[192:193]
	v_pk_mul_f32 v[94:95], v[90:91], v[94:95]
	v_pk_mul_f32 v[96:97], v[92:93], v[96:97]
	v_cvt_pk_f16_f32 v94, v94, v95
	v_cvt_pk_f16_f32 v95, v96, v97
	global_store_dwordx2 v183, v[94:95], s[96:97]
	v_pk_mul_f32 v[86:87], v[86:87], v[146:147]
	v_pk_mul_f32 v[88:89], v[88:89], v[148:149]
	v_pk_mul_f32 v[190:191], v[186:187], v[142:143] op_sel_hi:[0,1]
	v_pk_mul_f32 v[192:193], v[186:187], v[144:145] op_sel_hi:[0,1]
	v_cvt_f32_f16_e32 v194, v156
	v_cvt_f32_f16_sdwa v195, v156 dst_sel:DWORD dst_unused:UNUSED_PAD src0_sel:WORD_1
	v_cvt_f32_f16_e32 v196, v157
	v_cvt_f32_f16_sdwa v197, v157 dst_sel:DWORD dst_unused:UNUSED_PAD src0_sel:WORD_1
	v_pk_fma_f32 v[86:87], v[190:191], v[194:195], v[86:87]
	v_pk_fma_f32 v[88:89], v[192:193], v[196:197], v[88:89]
	v_pk_mul_f32 v[190:191], v[188:189], v[150:151] op_sel_hi:[0,1]
	v_pk_mul_f32 v[192:193], v[188:189], v[152:153] op_sel_hi:[0,1]
	v_cvt_f32_f16_e32 v194, v160
	v_cvt_f32_f16_sdwa v195, v160 dst_sel:DWORD dst_unused:UNUSED_PAD src0_sel:WORD_1
	v_cvt_f32_f16_e32 v196, v161
	v_cvt_f32_f16_sdwa v197, v161 dst_sel:DWORD dst_unused:UNUSED_PAD src0_sel:WORD_1
	v_pk_fma_f32 v[86:87], v[190:191], v[194:195], v[86:87]
	v_pk_fma_f32 v[88:89], v[192:193], v[196:197], v[88:89]
	v_mul_f32_e32 v190, 0xbfb8aa3b, v86
	v_mul_f32_e32 v191, 0xbfb8aa3b, v87
	v_mul_f32_e32 v192, 0xbfb8aa3b, v88
	v_mul_f32_e32 v193, 0xbfb8aa3b, v89
	v_exp_f32_e32 v190, v190
	v_exp_f32_e32 v191, v191
	v_exp_f32_e32 v192, v192
	v_exp_f32_e32 v193, v193
	v_add_f32_e32 v190, 1.0, v190
	v_add_f32_e32 v191, 1.0, v191
	v_add_f32_e32 v192, 1.0, v192
	v_add_f32_e32 v193, 1.0, v193
	v_rcp_f32_e32 v190, v190
	v_rcp_f32_e32 v191, v191
	v_rcp_f32_e32 v192, v192
	v_rcp_f32_e32 v193, v193
	s_nop 0
	v_pk_mul_f32 v[86:87], v[86:87], v[190:191]
	v_pk_mul_f32 v[88:89], v[88:89], v[192:193]
	v_pk_mul_f32 v[86:87], v[82:83], v[86:87]
	v_pk_mul_f32 v[88:89], v[84:85], v[88:89]
	v_cvt_pk_f16_f32 v86, v86, v87
	v_cvt_pk_f16_f32 v87, v88, v89
	global_store_dwordx2 v183, v[86:87], s[96:97] offset:32
	s_mov_b64 exec, s[4:5]
	v_add_u32_e32 v179, 0x4400, v201
	ds_read2_b64 v[154:157], v179 offset1:4
	ds_read2_b64 v[158:161], v179 offset0:68 offset1:72
	v_add_u32_e32 v180, 48, v200
	v_add_u32_e32 v181, s34, v180
	v_add_u32_e32 v182, -1, v180
	v_cmp_gt_u32_e32 vcc, 0xfe, v182
	v_cmp_gt_i32_e64 s[2:3], s6, v181
	v_cmp_gt_i32_e64 s[4:5], s68, v181
	v_mad_u32_u24 v183, v181, s52, v207
	s_and_b64 s[2:3], vcc, s[2:3]
	v_cndmask_b32_e64 v184, v216, v217, s[4:5]
	v_and_b32_e32 v185, v184, v181
	v_cmp_eq_u32_e32 vcc, 0, v185
	s_nop 1
	v_cndmask_b32_e64 v186, 1.0, 0, vcc
	v_cmp_eq_u32_e32 vcc, v185, v184
	s_nop 1
	v_cndmask_b32_e64 v188, 1.0, 0, vcc
	s_and_saveexec_b64 s[4:5], s[2:3]
	s_waitcnt lgkmcnt(2)
	v_pk_mul_f32 v[78:79], v[78:79], v[134:135]
	v_pk_mul_f32 v[80:81], v[80:81], v[136:137]
	v_pk_mul_f32 v[190:191], v[186:187], v[130:131] op_sel_hi:[0,1]
	v_pk_mul_f32 v[192:193], v[186:187], v[132:133] op_sel_hi:[0,1]
	v_cvt_f32_f16_e32 v194, v162
	v_cvt_f32_f16_sdwa v195, v162 dst_sel:DWORD dst_unused:UNUSED_PAD src0_sel:WORD_1
	v_cvt_f32_f16_e32 v196, v163
	v_cvt_f32_f16_sdwa v197, v163 dst_sel:DWORD dst_unused:UNUSED_PAD src0_sel:WORD_1
	v_pk_fma_f32 v[78:79], v[190:191], v[194:195], v[78:79]
	v_pk_fma_f32 v[80:81], v[192:193], v[196:197], v[80:81]
	v_pk_mul_f32 v[190:191], v[188:189], v[138:139] op_sel_hi:[0,1]
	v_pk_mul_f32 v[192:193], v[188:189], v[140:141] op_sel_hi:[0,1]
	v_cvt_f32_f16_e32 v194, v166
	v_cvt_f32_f16_sdwa v195, v166 dst_sel:DWORD dst_unused:UNUSED_PAD src0_sel:WORD_1
	v_cvt_f32_f16_e32 v196, v167
	v_cvt_f32_f16_sdwa v197, v167 dst_sel:DWORD dst_unused:UNUSED_PAD src0_sel:WORD_1
	v_pk_fma_f32 v[78:79], v[190:191], v[194:195], v[78:79]
	v_pk_fma_f32 v[80:81], v[192:193], v[196:197], v[80:81]
	v_mul_f32_e32 v190, 0xbfb8aa3b, v78
	v_mul_f32_e32 v191, 0xbfb8aa3b, v79
	v_mul_f32_e32 v192, 0xbfb8aa3b, v80
	v_mul_f32_e32 v193, 0xbfb8aa3b, v81
	v_exp_f32_e32 v190, v190
	v_exp_f32_e32 v191, v191
	v_exp_f32_e32 v192, v192
	v_exp_f32_e32 v193, v193
	v_add_f32_e32 v190, 1.0, v190
	v_add_f32_e32 v191, 1.0, v191
	v_add_f32_e32 v192, 1.0, v192
	v_add_f32_e32 v193, 1.0, v193
	v_rcp_f32_e32 v190, v190
	v_rcp_f32_e32 v191, v191
	v_rcp_f32_e32 v192, v192
	v_rcp_f32_e32 v193, v193
	s_nop 0
	v_pk_mul_f32 v[78:79], v[78:79], v[190:191]
	v_pk_mul_f32 v[80:81], v[80:81], v[192:193]
	v_pk_mul_f32 v[78:79], v[74:75], v[78:79]
	v_pk_mul_f32 v[80:81], v[76:77], v[80:81]
	v_cvt_pk_f16_f32 v78, v78, v79
	v_cvt_pk_f16_f32 v79, v80, v81
	global_store_dwordx2 v183, v[78:79], s[96:97]
	v_pk_mul_f32 v[70:71], v[70:71], v[146:147]
	v_pk_mul_f32 v[72:73], v[72:73], v[148:149]
	v_pk_mul_f32 v[190:191], v[186:187], v[142:143] op_sel_hi:[0,1]
	v_pk_mul_f32 v[192:193], v[186:187], v[144:145] op_sel_hi:[0,1]
	v_cvt_f32_f16_e32 v194, v164
	v_cvt_f32_f16_sdwa v195, v164 dst_sel:DWORD dst_unused:UNUSED_PAD src0_sel:WORD_1
	v_cvt_f32_f16_e32 v196, v165
	v_cvt_f32_f16_sdwa v197, v165 dst_sel:DWORD dst_unused:UNUSED_PAD src0_sel:WORD_1
	v_pk_fma_f32 v[70:71], v[190:191], v[194:195], v[70:71]
	v_pk_fma_f32 v[72:73], v[192:193], v[196:197], v[72:73]
	v_pk_mul_f32 v[190:191], v[188:189], v[150:151] op_sel_hi:[0,1]
	v_pk_mul_f32 v[192:193], v[188:189], v[152:153] op_sel_hi:[0,1]
	v_cvt_f32_f16_e32 v194, v168
	v_cvt_f32_f16_sdwa v195, v168 dst_sel:DWORD dst_unused:UNUSED_PAD src0_sel:WORD_1
	v_cvt_f32_f16_e32 v196, v169
	v_cvt_f32_f16_sdwa v197, v169 dst_sel:DWORD dst_unused:UNUSED_PAD src0_sel:WORD_1
	v_pk_fma_f32 v[70:71], v[190:191], v[194:195], v[70:71]
	v_pk_fma_f32 v[72:73], v[192:193], v[196:197], v[72:73]
	v_mul_f32_e32 v190, 0xbfb8aa3b, v70
	v_mul_f32_e32 v191, 0xbfb8aa3b, v71
	v_mul_f32_e32 v192, 0xbfb8aa3b, v72
	v_mul_f32_e32 v193, 0xbfb8aa3b, v73
	v_exp_f32_e32 v190, v190
	v_exp_f32_e32 v191, v191
	v_exp_f32_e32 v192, v192
	v_exp_f32_e32 v193, v193
	v_add_f32_e32 v190, 1.0, v190
	v_add_f32_e32 v191, 1.0, v191
	v_add_f32_e32 v192, 1.0, v192
	v_add_f32_e32 v193, 1.0, v193
	v_rcp_f32_e32 v190, v190
	v_rcp_f32_e32 v191, v191
	v_rcp_f32_e32 v192, v192
	v_rcp_f32_e32 v193, v193
	s_nop 0
	v_pk_mul_f32 v[70:71], v[70:71], v[190:191]
	v_pk_mul_f32 v[72:73], v[72:73], v[192:193]
	v_pk_mul_f32 v[70:71], v[66:67], v[70:71]
	v_pk_mul_f32 v[72:73], v[68:69], v[72:73]
	v_cvt_pk_f16_f32 v70, v70, v71
	v_cvt_pk_f16_f32 v71, v72, v73
	global_store_dwordx2 v183, v[70:71], s[96:97] offset:32
	s_mov_b64 exec, s[4:5]
	v_add_u32_e32 v179, 0x5500, v201
	ds_read2_b64 v[162:165], v179 offset1:4
	ds_read2_b64 v[166:169], v179 offset0:68 offset1:72
	v_add_u32_e32 v180, 64, v200
	v_add_u32_e32 v181, s34, v180
	v_add_u32_e32 v182, -1, v180
	v_cmp_gt_u32_e32 vcc, 0xfe, v182
	v_cmp_gt_i32_e64 s[2:3], s6, v181
	v_cmp_gt_i32_e64 s[4:5], s68, v181
	v_mad_u32_u24 v183, v181, s52, v207
	s_and_b64 s[2:3], vcc, s[2:3]
	v_cndmask_b32_e64 v184, v216, v217, s[4:5]
	v_and_b32_e32 v185, v184, v181
	v_cmp_eq_u32_e32 vcc, 0, v185
	s_nop 1
	v_cndmask_b32_e64 v186, 1.0, 0, vcc
	v_cmp_eq_u32_e32 vcc, v185, v184
	s_nop 1
	v_cndmask_b32_e64 v188, 1.0, 0, vcc
	s_and_saveexec_b64 s[4:5], s[2:3]
	s_waitcnt lgkmcnt(2)
	v_pk_mul_f32 v[62:63], v[62:63], v[134:135]
	v_pk_mul_f32 v[64:65], v[64:65], v[136:137]
	v_pk_mul_f32 v[190:191], v[186:187], v[130:131] op_sel_hi:[0,1]
	v_pk_mul_f32 v[192:193], v[186:187], v[132:133] op_sel_hi:[0,1]
	v_cvt_f32_f16_e32 v194, v154
	v_cvt_f32_f16_sdwa v195, v154 dst_sel:DWORD dst_unused:UNUSED_PAD src0_sel:WORD_1
	v_cvt_f32_f16_e32 v196, v155
	v_cvt_f32_f16_sdwa v197, v155 dst_sel:DWORD dst_unused:UNUSED_PAD src0_sel:WORD_1
	v_pk_fma_f32 v[62:63], v[190:191], v[194:195], v[62:63]
	v_pk_fma_f32 v[64:65], v[192:193], v[196:197], v[64:65]
	v_pk_mul_f32 v[190:191], v[188:189], v[138:139] op_sel_hi:[0,1]
	v_pk_mul_f32 v[192:193], v[188:189], v[140:141] op_sel_hi:[0,1]
	v_cvt_f32_f16_e32 v194, v158
	v_cvt_f32_f16_sdwa v195, v158 dst_sel:DWORD dst_unused:UNUSED_PAD src0_sel:WORD_1
	v_cvt_f32_f16_e32 v196, v159
	v_cvt_f32_f16_sdwa v197, v159 dst_sel:DWORD dst_unused:UNUSED_PAD src0_sel:WORD_1
	v_pk_fma_f32 v[62:63], v[190:191], v[194:195], v[62:63]
	v_pk_fma_f32 v[64:65], v[192:193], v[196:197], v[64:65]
	v_mul_f32_e32 v190, 0xbfb8aa3b, v62
	v_mul_f32_e32 v191, 0xbfb8aa3b, v63
	v_mul_f32_e32 v192, 0xbfb8aa3b, v64
	v_mul_f32_e32 v193, 0xbfb8aa3b, v65
	v_exp_f32_e32 v190, v190
	v_exp_f32_e32 v191, v191
	v_exp_f32_e32 v192, v192
	v_exp_f32_e32 v193, v193
	v_add_f32_e32 v190, 1.0, v190
	v_add_f32_e32 v191, 1.0, v191
	v_add_f32_e32 v192, 1.0, v192
	v_add_f32_e32 v193, 1.0, v193
	v_rcp_f32_e32 v190, v190
	v_rcp_f32_e32 v191, v191
	v_rcp_f32_e32 v192, v192
	v_rcp_f32_e32 v193, v193
	s_nop 0
	v_pk_mul_f32 v[62:63], v[62:63], v[190:191]
	v_pk_mul_f32 v[64:65], v[64:65], v[192:193]
	v_pk_mul_f32 v[62:63], v[58:59], v[62:63]
	v_pk_mul_f32 v[64:65], v[60:61], v[64:65]
	v_cvt_pk_f16_f32 v62, v62, v63
	v_cvt_pk_f16_f32 v63, v64, v65
	global_store_dwordx2 v183, v[62:63], s[96:97]
	v_pk_mul_f32 v[54:55], v[54:55], v[146:147]
	v_pk_mul_f32 v[56:57], v[56:57], v[148:149]
	v_pk_mul_f32 v[190:191], v[186:187], v[142:143] op_sel_hi:[0,1]
	v_pk_mul_f32 v[192:193], v[186:187], v[144:145] op_sel_hi:[0,1]
	v_cvt_f32_f16_e32 v194, v156
	v_cvt_f32_f16_sdwa v195, v156 dst_sel:DWORD dst_unused:UNUSED_PAD src0_sel:WORD_1
	v_cvt_f32_f16_e32 v196, v157
	v_cvt_f32_f16_sdwa v197, v157 dst_sel:DWORD dst_unused:UNUSED_PAD src0_sel:WORD_1
	v_pk_fma_f32 v[54:55], v[190:191], v[194:195], v[54:55]
	v_pk_fma_f32 v[56:57], v[192:193], v[196:197], v[56:57]
	v_pk_mul_f32 v[190:191], v[188:189], v[150:151] op_sel_hi:[0,1]
	v_pk_mul_f32 v[192:193], v[188:189], v[152:153] op_sel_hi:[0,1]
	v_cvt_f32_f16_e32 v194, v160
	v_cvt_f32_f16_sdwa v195, v160 dst_sel:DWORD dst_unused:UNUSED_PAD src0_sel:WORD_1
	v_cvt_f32_f16_e32 v196, v161
	v_cvt_f32_f16_sdwa v197, v161 dst_sel:DWORD dst_unused:UNUSED_PAD src0_sel:WORD_1
	v_pk_fma_f32 v[54:55], v[190:191], v[194:195], v[54:55]
	v_pk_fma_f32 v[56:57], v[192:193], v[196:197], v[56:57]
	v_mul_f32_e32 v190, 0xbfb8aa3b, v54
	v_mul_f32_e32 v191, 0xbfb8aa3b, v55
	v_mul_f32_e32 v192, 0xbfb8aa3b, v56
	v_mul_f32_e32 v193, 0xbfb8aa3b, v57
	v_exp_f32_e32 v190, v190
	v_exp_f32_e32 v191, v191
	v_exp_f32_e32 v192, v192
	v_exp_f32_e32 v193, v193
	v_add_f32_e32 v190, 1.0, v190
	v_add_f32_e32 v191, 1.0, v191
	v_add_f32_e32 v192, 1.0, v192
	v_add_f32_e32 v193, 1.0, v193
	v_rcp_f32_e32 v190, v190
	v_rcp_f32_e32 v191, v191
	v_rcp_f32_e32 v192, v192
	v_rcp_f32_e32 v193, v193
	s_nop 0
	v_pk_mul_f32 v[54:55], v[54:55], v[190:191]
	v_pk_mul_f32 v[56:57], v[56:57], v[192:193]
	v_pk_mul_f32 v[54:55], v[50:51], v[54:55]
	v_pk_mul_f32 v[56:57], v[52:53], v[56:57]
	v_cvt_pk_f16_f32 v54, v54, v55
	v_cvt_pk_f16_f32 v55, v56, v57
	global_store_dwordx2 v183, v[54:55], s[96:97] offset:32
	s_mov_b64 exec, s[4:5]
	v_add_u32_e32 v179, 0x6600, v201
	ds_read2_b64 v[154:157], v179 offset1:4
	ds_read2_b64 v[158:161], v179 offset0:68 offset1:72
	v_add_u32_e32 v180, 80, v200
	v_add_u32_e32 v181, s34, v180
	v_add_u32_e32 v182, -1, v180
	v_cmp_gt_u32_e32 vcc, 0xfe, v182
	v_cmp_gt_i32_e64 s[2:3], s6, v181
	v_cmp_gt_i32_e64 s[4:5], s68, v181
	v_mad_u32_u24 v183, v181, s52, v207
	s_and_b64 s[2:3], vcc, s[2:3]
	v_cndmask_b32_e64 v184, v216, v217, s[4:5]
	v_and_b32_e32 v185, v184, v181
	v_cmp_eq_u32_e32 vcc, 0, v185
	s_nop 1
	v_cndmask_b32_e64 v186, 1.0, 0, vcc
	v_cmp_eq_u32_e32 vcc, v185, v184
	s_nop 1
	v_cndmask_b32_e64 v188, 1.0, 0, vcc
	s_and_saveexec_b64 s[4:5], s[2:3]
	s_waitcnt lgkmcnt(2)
	v_pk_mul_f32 v[46:47], v[46:47], v[134:135]
	v_pk_mul_f32 v[48:49], v[48:49], v[136:137]
	v_pk_mul_f32 v[190:191], v[186:187], v[130:131] op_sel_hi:[0,1]
	v_pk_mul_f32 v[192:193], v[186:187], v[132:133] op_sel_hi:[0,1]
	v_cvt_f32_f16_e32 v194, v162
	v_cvt_f32_f16_sdwa v195, v162 dst_sel:DWORD dst_unused:UNUSED_PAD src0_sel:WORD_1
	v_cvt_f32_f16_e32 v196, v163
	v_cvt_f32_f16_sdwa v197, v163 dst_sel:DWORD dst_unused:UNUSED_PAD src0_sel:WORD_1
	v_pk_fma_f32 v[46:47], v[190:191], v[194:195], v[46:47]
	v_pk_fma_f32 v[48:49], v[192:193], v[196:197], v[48:49]
	v_pk_mul_f32 v[190:191], v[188:189], v[138:139] op_sel_hi:[0,1]
	v_pk_mul_f32 v[192:193], v[188:189], v[140:141] op_sel_hi:[0,1]
	v_cvt_f32_f16_e32 v194, v166
	v_cvt_f32_f16_sdwa v195, v166 dst_sel:DWORD dst_unused:UNUSED_PAD src0_sel:WORD_1
	v_cvt_f32_f16_e32 v196, v167
	v_cvt_f32_f16_sdwa v197, v167 dst_sel:DWORD dst_unused:UNUSED_PAD src0_sel:WORD_1
	v_pk_fma_f32 v[46:47], v[190:191], v[194:195], v[46:47]
	v_pk_fma_f32 v[48:49], v[192:193], v[196:197], v[48:49]
	v_mul_f32_e32 v190, 0xbfb8aa3b, v46
	v_mul_f32_e32 v191, 0xbfb8aa3b, v47
	v_mul_f32_e32 v192, 0xbfb8aa3b, v48
	v_mul_f32_e32 v193, 0xbfb8aa3b, v49
	v_exp_f32_e32 v190, v190
	v_exp_f32_e32 v191, v191
	v_exp_f32_e32 v192, v192
	v_exp_f32_e32 v193, v193
	v_add_f32_e32 v190, 1.0, v190
	v_add_f32_e32 v191, 1.0, v191
	v_add_f32_e32 v192, 1.0, v192
	v_add_f32_e32 v193, 1.0, v193
	v_rcp_f32_e32 v190, v190
	v_rcp_f32_e32 v191, v191
	v_rcp_f32_e32 v192, v192
	v_rcp_f32_e32 v193, v193
	s_nop 0
	v_pk_mul_f32 v[46:47], v[46:47], v[190:191]
	v_pk_mul_f32 v[48:49], v[48:49], v[192:193]
	v_pk_mul_f32 v[46:47], v[42:43], v[46:47]
	v_pk_mul_f32 v[48:49], v[44:45], v[48:49]
	v_cvt_pk_f16_f32 v46, v46, v47
	v_cvt_pk_f16_f32 v47, v48, v49
	global_store_dwordx2 v183, v[46:47], s[96:97]
	v_pk_mul_f32 v[38:39], v[38:39], v[146:147]
	v_pk_mul_f32 v[40:41], v[40:41], v[148:149]
	v_pk_mul_f32 v[190:191], v[186:187], v[142:143] op_sel_hi:[0,1]
	v_pk_mul_f32 v[192:193], v[186:187], v[144:145] op_sel_hi:[0,1]
	v_cvt_f32_f16_e32 v194, v164
	v_cvt_f32_f16_sdwa v195, v164 dst_sel:DWORD dst_unused:UNUSED_PAD src0_sel:WORD_1
	v_cvt_f32_f16_e32 v196, v165
	v_cvt_f32_f16_sdwa v197, v165 dst_sel:DWORD dst_unused:UNUSED_PAD src0_sel:WORD_1
	v_pk_fma_f32 v[38:39], v[190:191], v[194:195], v[38:39]
	v_pk_fma_f32 v[40:41], v[192:193], v[196:197], v[40:41]
	v_pk_mul_f32 v[190:191], v[188:189], v[150:151] op_sel_hi:[0,1]
	v_pk_mul_f32 v[192:193], v[188:189], v[152:153] op_sel_hi:[0,1]
	v_cvt_f32_f16_e32 v194, v168
	v_cvt_f32_f16_sdwa v195, v168 dst_sel:DWORD dst_unused:UNUSED_PAD src0_sel:WORD_1
	v_cvt_f32_f16_e32 v196, v169
	v_cvt_f32_f16_sdwa v197, v169 dst_sel:DWORD dst_unused:UNUSED_PAD src0_sel:WORD_1
	v_pk_fma_f32 v[38:39], v[190:191], v[194:195], v[38:39]
	v_pk_fma_f32 v[40:41], v[192:193], v[196:197], v[40:41]
	v_mul_f32_e32 v190, 0xbfb8aa3b, v38
	v_mul_f32_e32 v191, 0xbfb8aa3b, v39
	v_mul_f32_e32 v192, 0xbfb8aa3b, v40
	v_mul_f32_e32 v193, 0xbfb8aa3b, v41
	v_exp_f32_e32 v190, v190
	v_exp_f32_e32 v191, v191
	v_exp_f32_e32 v192, v192
	v_exp_f32_e32 v193, v193
	v_add_f32_e32 v190, 1.0, v190
	v_add_f32_e32 v191, 1.0, v191
	v_add_f32_e32 v192, 1.0, v192
	v_add_f32_e32 v193, 1.0, v193
	v_rcp_f32_e32 v190, v190
	v_rcp_f32_e32 v191, v191
	v_rcp_f32_e32 v192, v192
	v_rcp_f32_e32 v193, v193
	s_nop 0
	v_pk_mul_f32 v[38:39], v[38:39], v[190:191]
	v_pk_mul_f32 v[40:41], v[40:41], v[192:193]
	v_pk_mul_f32 v[38:39], v[34:35], v[38:39]
	v_pk_mul_f32 v[40:41], v[36:37], v[40:41]
	v_cvt_pk_f16_f32 v38, v38, v39
	v_cvt_pk_f16_f32 v39, v40, v41
	global_store_dwordx2 v183, v[38:39], s[96:97] offset:32
	s_mov_b64 exec, s[4:5]
	v_add_u32_e32 v179, 0x7700, v201
	ds_read2_b64 v[162:165], v179 offset1:4
	ds_read2_b64 v[166:169], v179 offset0:68 offset1:72
	v_add_u32_e32 v180, 96, v200
	v_add_u32_e32 v181, s34, v180
	v_add_u32_e32 v182, -1, v180
	v_cmp_gt_u32_e32 vcc, 0xfe, v182
	v_cmp_gt_i32_e64 s[2:3], s6, v181
	v_cmp_gt_i32_e64 s[4:5], s68, v181
	v_mad_u32_u24 v183, v181, s52, v207
	s_and_b64 s[2:3], vcc, s[2:3]
	v_cndmask_b32_e64 v184, v216, v217, s[4:5]
	v_and_b32_e32 v185, v184, v181
	v_cmp_eq_u32_e32 vcc, 0, v185
	s_nop 1
	v_cndmask_b32_e64 v186, 1.0, 0, vcc
	v_cmp_eq_u32_e32 vcc, v185, v184
	s_nop 1
	v_cndmask_b32_e64 v188, 1.0, 0, vcc
	s_and_saveexec_b64 s[4:5], s[2:3]
	s_waitcnt lgkmcnt(2)
	v_pk_mul_f32 v[30:31], v[30:31], v[134:135]
	v_pk_mul_f32 v[32:33], v[32:33], v[136:137]
	v_pk_mul_f32 v[190:191], v[186:187], v[130:131] op_sel_hi:[0,1]
	v_pk_mul_f32 v[192:193], v[186:187], v[132:133] op_sel_hi:[0,1]
	v_cvt_f32_f16_e32 v194, v154
	v_cvt_f32_f16_sdwa v195, v154 dst_sel:DWORD dst_unused:UNUSED_PAD src0_sel:WORD_1
	v_cvt_f32_f16_e32 v196, v155
	v_cvt_f32_f16_sdwa v197, v155 dst_sel:DWORD dst_unused:UNUSED_PAD src0_sel:WORD_1
	v_pk_fma_f32 v[30:31], v[190:191], v[194:195], v[30:31]
	v_pk_fma_f32 v[32:33], v[192:193], v[196:197], v[32:33]
	v_pk_mul_f32 v[190:191], v[188:189], v[138:139] op_sel_hi:[0,1]
	v_pk_mul_f32 v[192:193], v[188:189], v[140:141] op_sel_hi:[0,1]
	v_cvt_f32_f16_e32 v194, v158
	v_cvt_f32_f16_sdwa v195, v158 dst_sel:DWORD dst_unused:UNUSED_PAD src0_sel:WORD_1
	v_cvt_f32_f16_e32 v196, v159
	v_cvt_f32_f16_sdwa v197, v159 dst_sel:DWORD dst_unused:UNUSED_PAD src0_sel:WORD_1
	v_pk_fma_f32 v[30:31], v[190:191], v[194:195], v[30:31]
	v_pk_fma_f32 v[32:33], v[192:193], v[196:197], v[32:33]
	v_mul_f32_e32 v190, 0xbfb8aa3b, v30
	v_mul_f32_e32 v191, 0xbfb8aa3b, v31
	v_mul_f32_e32 v192, 0xbfb8aa3b, v32
	v_mul_f32_e32 v193, 0xbfb8aa3b, v33
	v_exp_f32_e32 v190, v190
	v_exp_f32_e32 v191, v191
	v_exp_f32_e32 v192, v192
	v_exp_f32_e32 v193, v193
	v_add_f32_e32 v190, 1.0, v190
	v_add_f32_e32 v191, 1.0, v191
	v_add_f32_e32 v192, 1.0, v192
	v_add_f32_e32 v193, 1.0, v193
	v_rcp_f32_e32 v190, v190
	v_rcp_f32_e32 v191, v191
	v_rcp_f32_e32 v192, v192
	v_rcp_f32_e32 v193, v193
	s_nop 0
	v_pk_mul_f32 v[30:31], v[30:31], v[190:191]
	v_pk_mul_f32 v[32:33], v[32:33], v[192:193]
	v_pk_mul_f32 v[30:31], v[26:27], v[30:31]
	v_pk_mul_f32 v[32:33], v[28:29], v[32:33]
	v_cvt_pk_f16_f32 v30, v30, v31
	v_cvt_pk_f16_f32 v31, v32, v33
	global_store_dwordx2 v183, v[30:31], s[96:97]
	v_pk_mul_f32 v[22:23], v[22:23], v[146:147]
	v_pk_mul_f32 v[24:25], v[24:25], v[148:149]
	v_pk_mul_f32 v[190:191], v[186:187], v[142:143] op_sel_hi:[0,1]
	v_pk_mul_f32 v[192:193], v[186:187], v[144:145] op_sel_hi:[0,1]
	v_cvt_f32_f16_e32 v194, v156
	v_cvt_f32_f16_sdwa v195, v156 dst_sel:DWORD dst_unused:UNUSED_PAD src0_sel:WORD_1
	v_cvt_f32_f16_e32 v196, v157
	v_cvt_f32_f16_sdwa v197, v157 dst_sel:DWORD dst_unused:UNUSED_PAD src0_sel:WORD_1
	v_pk_fma_f32 v[22:23], v[190:191], v[194:195], v[22:23]
	v_pk_fma_f32 v[24:25], v[192:193], v[196:197], v[24:25]
	v_pk_mul_f32 v[190:191], v[188:189], v[150:151] op_sel_hi:[0,1]
	v_pk_mul_f32 v[192:193], v[188:189], v[152:153] op_sel_hi:[0,1]
	v_cvt_f32_f16_e32 v194, v160
	v_cvt_f32_f16_sdwa v195, v160 dst_sel:DWORD dst_unused:UNUSED_PAD src0_sel:WORD_1
	v_cvt_f32_f16_e32 v196, v161
	v_cvt_f32_f16_sdwa v197, v161 dst_sel:DWORD dst_unused:UNUSED_PAD src0_sel:WORD_1
	v_pk_fma_f32 v[22:23], v[190:191], v[194:195], v[22:23]
	v_pk_fma_f32 v[24:25], v[192:193], v[196:197], v[24:25]
	v_mul_f32_e32 v190, 0xbfb8aa3b, v22
	v_mul_f32_e32 v191, 0xbfb8aa3b, v23
	v_mul_f32_e32 v192, 0xbfb8aa3b, v24
	v_mul_f32_e32 v193, 0xbfb8aa3b, v25
	v_exp_f32_e32 v190, v190
	v_exp_f32_e32 v191, v191
	v_exp_f32_e32 v192, v192
	v_exp_f32_e32 v193, v193
	v_add_f32_e32 v190, 1.0, v190
	v_add_f32_e32 v191, 1.0, v191
	v_add_f32_e32 v192, 1.0, v192
	v_add_f32_e32 v193, 1.0, v193
	v_rcp_f32_e32 v190, v190
	v_rcp_f32_e32 v191, v191
	v_rcp_f32_e32 v192, v192
	v_rcp_f32_e32 v193, v193
	s_nop 0
	v_pk_mul_f32 v[22:23], v[22:23], v[190:191]
	v_pk_mul_f32 v[24:25], v[24:25], v[192:193]
	v_pk_mul_f32 v[22:23], v[18:19], v[22:23]
	v_pk_mul_f32 v[24:25], v[20:21], v[24:25]
	v_cvt_pk_f16_f32 v22, v22, v23
	v_cvt_pk_f16_f32 v23, v24, v25
	global_store_dwordx2 v183, v[22:23], s[96:97] offset:32
	s_mov_b64 exec, s[4:5]
	v_add_u32_e32 v180, 112, v200
	v_add_u32_e32 v181, s34, v180
	v_add_u32_e32 v182, -1, v180
	v_cmp_gt_u32_e32 vcc, 0xfe, v182
	v_cmp_gt_i32_e64 s[2:3], s6, v181
	v_cmp_gt_i32_e64 s[4:5], s68, v181
	v_mad_u32_u24 v183, v181, s52, v207
	s_and_b64 s[2:3], vcc, s[2:3]
	v_cndmask_b32_e64 v184, v216, v217, s[4:5]
	v_and_b32_e32 v185, v184, v181
	v_cmp_eq_u32_e32 vcc, 0, v185
	s_nop 1
	v_cndmask_b32_e64 v186, 1.0, 0, vcc
	v_cmp_eq_u32_e32 vcc, v185, v184
	s_nop 1
	v_cndmask_b32_e64 v188, 1.0, 0, vcc
	s_and_saveexec_b64 s[4:5], s[2:3]
	s_waitcnt lgkmcnt(0)
	v_pk_mul_f32 v[14:15], v[14:15], v[134:135]
	v_pk_mul_f32 v[16:17], v[16:17], v[136:137]
	v_pk_mul_f32 v[190:191], v[186:187], v[130:131] op_sel_hi:[0,1]
	v_pk_mul_f32 v[192:193], v[186:187], v[132:133] op_sel_hi:[0,1]
	v_cvt_f32_f16_e32 v194, v162
	v_cvt_f32_f16_sdwa v195, v162 dst_sel:DWORD dst_unused:UNUSED_PAD src0_sel:WORD_1
	v_cvt_f32_f16_e32 v196, v163
	v_cvt_f32_f16_sdwa v197, v163 dst_sel:DWORD dst_unused:UNUSED_PAD src0_sel:WORD_1
	v_pk_fma_f32 v[14:15], v[190:191], v[194:195], v[14:15]
	v_pk_fma_f32 v[16:17], v[192:193], v[196:197], v[16:17]
	v_pk_mul_f32 v[190:191], v[188:189], v[138:139] op_sel_hi:[0,1]
	v_pk_mul_f32 v[192:193], v[188:189], v[140:141] op_sel_hi:[0,1]
	v_cvt_f32_f16_e32 v194, v166
	v_cvt_f32_f16_sdwa v195, v166 dst_sel:DWORD dst_unused:UNUSED_PAD src0_sel:WORD_1
	v_cvt_f32_f16_e32 v196, v167
	v_cvt_f32_f16_sdwa v197, v167 dst_sel:DWORD dst_unused:UNUSED_PAD src0_sel:WORD_1
	v_pk_fma_f32 v[14:15], v[190:191], v[194:195], v[14:15]
	v_pk_fma_f32 v[16:17], v[192:193], v[196:197], v[16:17]
	v_mul_f32_e32 v190, 0xbfb8aa3b, v14
	v_mul_f32_e32 v191, 0xbfb8aa3b, v15
	v_mul_f32_e32 v192, 0xbfb8aa3b, v16
	v_mul_f32_e32 v193, 0xbfb8aa3b, v17
	v_exp_f32_e32 v190, v190
	v_exp_f32_e32 v191, v191
	v_exp_f32_e32 v192, v192
	v_exp_f32_e32 v193, v193
	v_add_f32_e32 v190, 1.0, v190
	v_add_f32_e32 v191, 1.0, v191
	v_add_f32_e32 v192, 1.0, v192
	v_add_f32_e32 v193, 1.0, v193
	v_rcp_f32_e32 v190, v190
	v_rcp_f32_e32 v191, v191
	v_rcp_f32_e32 v192, v192
	v_rcp_f32_e32 v193, v193
	s_nop 0
	v_pk_mul_f32 v[14:15], v[14:15], v[190:191]
	v_pk_mul_f32 v[16:17], v[16:17], v[192:193]
	v_pk_mul_f32 v[14:15], v[10:11], v[14:15]
	v_pk_mul_f32 v[16:17], v[12:13], v[16:17]
	v_cvt_pk_f16_f32 v14, v14, v15
	v_cvt_pk_f16_f32 v15, v16, v17
	global_store_dwordx2 v183, v[14:15], s[96:97]
	v_pk_mul_f32 v[6:7], v[6:7], v[146:147]
	v_pk_mul_f32 v[8:9], v[8:9], v[148:149]
	v_pk_mul_f32 v[190:191], v[186:187], v[142:143] op_sel_hi:[0,1]
	v_pk_mul_f32 v[192:193], v[186:187], v[144:145] op_sel_hi:[0,1]
	v_cvt_f32_f16_e32 v194, v164
	v_cvt_f32_f16_sdwa v195, v164 dst_sel:DWORD dst_unused:UNUSED_PAD src0_sel:WORD_1
	v_cvt_f32_f16_e32 v196, v165
	v_cvt_f32_f16_sdwa v197, v165 dst_sel:DWORD dst_unused:UNUSED_PAD src0_sel:WORD_1
	v_pk_fma_f32 v[6:7], v[190:191], v[194:195], v[6:7]
	v_pk_fma_f32 v[8:9], v[192:193], v[196:197], v[8:9]
	v_pk_mul_f32 v[190:191], v[188:189], v[150:151] op_sel_hi:[0,1]
	v_pk_mul_f32 v[192:193], v[188:189], v[152:153] op_sel_hi:[0,1]
	v_cvt_f32_f16_e32 v194, v168
	v_cvt_f32_f16_sdwa v195, v168 dst_sel:DWORD dst_unused:UNUSED_PAD src0_sel:WORD_1
	v_cvt_f32_f16_e32 v196, v169
	v_cvt_f32_f16_sdwa v197, v169 dst_sel:DWORD dst_unused:UNUSED_PAD src0_sel:WORD_1
	v_pk_fma_f32 v[6:7], v[190:191], v[194:195], v[6:7]
	v_pk_fma_f32 v[8:9], v[192:193], v[196:197], v[8:9]
	v_mul_f32_e32 v190, 0xbfb8aa3b, v6
	v_mul_f32_e32 v191, 0xbfb8aa3b, v7
	v_mul_f32_e32 v192, 0xbfb8aa3b, v8
	v_mul_f32_e32 v193, 0xbfb8aa3b, v9
	v_exp_f32_e32 v190, v190
	v_exp_f32_e32 v191, v191
	v_exp_f32_e32 v192, v192
	v_exp_f32_e32 v193, v193
	v_add_f32_e32 v190, 1.0, v190
	v_add_f32_e32 v191, 1.0, v191
	v_add_f32_e32 v192, 1.0, v192
	v_add_f32_e32 v193, 1.0, v193
	v_rcp_f32_e32 v190, v190
	v_rcp_f32_e32 v191, v191
	v_rcp_f32_e32 v192, v192
	v_rcp_f32_e32 v193, v193
	s_nop 0
	v_pk_mul_f32 v[6:7], v[6:7], v[190:191]
	v_pk_mul_f32 v[8:9], v[8:9], v[192:193]
	v_pk_mul_f32 v[6:7], v[2:3], v[6:7]
	v_pk_mul_f32 v[8:9], v[4:5], v[8:9]
	v_cvt_pk_f16_f32 v6, v6, v7
	v_cvt_pk_f16_f32 v7, v8, v9
	global_store_dwordx2 v183, v[6:7], s[96:97] offset:32
	s_mov_b64 exec, s[4:5]
	s_cmp_lg_u32 s35, 0
	s_cbranch_scc1 .Lp4_cont
	s_branch .LBB0_1135

	.amdhsa_kernel _Z11mega_kernel5KArgs
		.amdhsa_group_segment_fixed_size 139264
		.amdhsa_private_segment_fixed_size 0
		.amdhsa_kernarg_size 448
		.amdhsa_user_sgpr_count 2
		.amdhsa_user_sgpr_dispatch_ptr 0
		.amdhsa_user_sgpr_queue_ptr 0
		.amdhsa_user_sgpr_kernarg_segment_ptr 1
		.amdhsa_user_sgpr_dispatch_id 0
		.amdhsa_user_sgpr_kernarg_preload_length 0
		.amdhsa_user_sgpr_kernarg_preload_offset 0
		.amdhsa_user_sgpr_private_segment_size 0
		.amdhsa_uses_dynamic_stack 0
		.amdhsa_enable_private_segment 0
		.amdhsa_system_sgpr_workgroup_id_x 1
		.amdhsa_system_sgpr_workgroup_id_y 0
		.amdhsa_system_sgpr_workgroup_id_z 0
		.amdhsa_system_sgpr_workgroup_info 0
		.amdhsa_system_vgpr_workitem_id 2
		.amdhsa_next_free_vgpr 256
		.amdhsa_next_free_sgpr 100
		.amdhsa_accum_offset 256
		.amdhsa_reserve_vcc 1
		.amdhsa_float_round_mode_32 0
		.amdhsa_float_round_mode_16_64 0
		.amdhsa_float_denorm_mode_32 3
		.amdhsa_float_denorm_mode_16_64 3
		.amdhsa_dx10_clamp 1
		.amdhsa_ieee_mode 1
		.amdhsa_fp16_overflow 0
		.amdhsa_tg_split 0
		.amdhsa_exception_fp_ieee_invalid_op 0
		.amdhsa_exception_fp_denorm_src 0
		.amdhsa_exception_fp_ieee_div_zero 0
		.amdhsa_exception_fp_ieee_overflow 0
		.amdhsa_exception_fp_ieee_underflow 0
		.amdhsa_exception_fp_ieee_inexact 0
		.amdhsa_exception_int_div_zero 0
	.end_amdhsa_kernel

amdhsa.kernels:
  - .agpr_count:     0
    .args:
      - .offset:         0
        .size:           192
        .value_kind:     by_value
      - .offset:         192
        .size:           4
        .value_kind:     hidden_block_count_x
      - .offset:         196
        .size:           4
        .value_kind:     hidden_block_count_y
      - .offset:         200
        .size:           4
        .value_kind:     hidden_block_count_z
      - .offset:         204
        .size:           2
        .value_kind:     hidden_group_size_x
      - .offset:         206
        .size:           2
        .value_kind:     hidden_group_size_y
      - .offset:         208
        .size:           2
        .value_kind:     hidden_group_size_z
      - .offset:         210
        .size:           2
        .value_kind:     hidden_remainder_x
      - .offset:         212
        .size:           2
        .value_kind:     hidden_remainder_y
      - .offset:         214
        .size:           2
        .value_kind:     hidden_remainder_z
      - .offset:         232
        .size:           8
        .value_kind:     hidden_global_offset_x
      - .offset:         240
        .size:           8
        .value_kind:     hidden_global_offset_y
      - .offset:         248
        .size:           8
        .value_kind:     hidden_global_offset_z
      - .offset:         256
        .size:           2
        .value_kind:     hidden_grid_dims
      - .offset:         280
        .size:           8
        .value_kind:     hidden_multigrid_sync_arg
    .group_segment_fixed_size: 139264
    .kernarg_segment_align: 8
    .kernarg_segment_size: 448
    .language:       OpenCL C
    .language_version:
      - 2
      - 0
    .max_flat_workgroup_size: 512
    .name:           _Z11mega_kernel5KArgs
    .private_segment_fixed_size: 0
    .sgpr_count:     106
    .sgpr_spill_count: 118
    .symbol:         _Z11mega_kernel5KArgs.kd
    .uniform_work_group_size: 1
    .uses_dynamic_stack: false
    .vgpr_count:     256
    .vgpr_spill_count: 0
    .wavefront_size: 64
